# v15 + EpiResid (FFN1-down, Wo, FFN2-down l0) epilogues: 14 of 16 residual-row loads hoisted to the epilogue top with conservative counted waits
# speedup vs baseline: 1.0080x; 1.0033x over previous
; __device__ __forceinline__ u32x2 pack4(f32x4 v) { u32x2 w; w.x = cvt_pk_bf16(v[0], v[1]); w.y = cvt_pk_bf16(v[2], v[3]); return w; }
;     __device__ __forceinline__ size_t goff(const Unit& u, int g, int wr, int wc, int fr, int fq) const { return (size_t)(u.pm * BM + (g >> 2) * HALF + wr * 64 + (g & 3) * 16 + fr) * 1024 + u.pn * BM + wc * 32 + fq * 8; }
;     __device__ __forceinline__ void gload(Grp& h, size_t off) const {
;         if constexpr (F32IN) { h.f[0] = *(const f32x4*)(hin + off); h.f[1] = *(const f32x4*)(hin + off + 4); h.f[2] = *(const f32x4*)(hin + off + HALF); h.f[3] = *(const f32x4*)(hin + off + HALF + 4); }
;         else { const u32x4 a = *(const u32x4*)(xa + off), b = *(const u32x4*)(xa + off + HALF); h.f[0] = __builtin_bit_cast(f32x4, a); h.f[2] = __builtin_bit_cast(f32x4, b); }
;     }
;     __device__ __forceinline__ void unpack(const Grp& h, int bj, f32x4& v0, f32x4& v1) const {
;         if constexpr (F32IN) { v0 = h.f[2 * bj]; v1 = h.f[2 * bj + 1]; }
;         else { const u32x4 w = __builtin_bit_cast(u32x4, h.f[2 * bj]);
;             v0[0] = __uint_as_float(w.x << 16); v0[1] = __uint_as_float(w.x & 0xffff0000u); v0[2] = __uint_as_float(w.y << 16); v0[3] = __uint_as_float(w.y & 0xffff0000u);
;             v1[0] = __uint_as_float(w.z << 16); v1[1] = __uint_as_float(w.z & 0xffff0000u); v1[2] = __uint_as_float(w.w << 16); v1[3] = __uint_as_float(w.w & 0xffff0000u); }
;     }
;     __device__ __forceinline__ void operator()(const f32x4 (&acc)[2][2][4][2], const Unit& u, int wr, int wc, int fr, int fq) const {
;         Grp h[2];
;         gload(h[0], goff(u, 0, wr, wc, fr, fq));
; #pragma unroll
;         for (int g = 0; g < 8; ++g) {
;             const int ai = g >> 2, m = g & 3; const size_t off = goff(u, g, wr, wc, fr, fq);
;             if (g < 7) gload(h[(g + 1) & 1], goff(u, g + 1, wr, wc, fr, fq));
;             float sq = 0.f;
; #pragma unroll
;             for (int bj = 0; bj < 2; ++bj) { const size_t o = off + bj * HALF; f32x4 h0, h1; unpack(h[g & 1], bj, h0, h1);
;                 h0 = h0 + acc[ai][bj][m][0] * alpha; h1 = h1 + acc[ai][bj][m][1] * alpha;
;                 const u32x2 p0 = pack4(h0), p1 = pack4(h1); u32x4 w; w.x = p0.x; w.y = p0.y; w.z = p1.x; w.w = p1.y; *(u32x4*)(xa + o) = w;
.LBB0_273:
	v_lshl_add_u32 v162, s4, 8, v157
	v_ashrrev_i32_e32 v163, 31, v162
	s_lshl_b32 s18, s56, 8
	s_ashr_i32 s19, s18, 31
	v_lshlrev_b64 v[128:129], 11, v[162:163]
	v_lshl_add_u64 v[128:129], s[22:23], 0, v[128:129]
	s_lshl_b64 s[16:17], s[18:19], 1
	v_lshl_add_u64 v[128:129], v[128:129], 0, s[16:17]
	s_lshl_b32 s4, s49, 1
	v_lshl_add_u64 v[128:129], v[128:129], 0, s[4:5]
	v_lshlrev_b32_e32 v144, 1, v156
	v_lshl_add_u64 v[180:181], v[128:129], 0, v[144:145]
	global_load_dwordx4 v[172:175], v[180:181], off
	global_load_dwordx4 v[176:179], v[180:181], off offset:256
	v_or_b32_e32 v164, 16, v162
	v_ashrrev_i32_e32 v165, 31, v164
	v_lshlrev_b64 v[128:129], 11, v[164:165]
	v_lshl_add_u64 v[128:129], s[22:23], 0, v[128:129]
	v_lshl_add_u64 v[128:129], v[128:129], 0, s[16:17]
	v_lshl_add_u64 v[128:129], v[128:129], 0, s[4:5]
	v_lshl_add_u64 v[166:167], v[128:129], 0, v[144:145]
	global_load_dwordx4 v[132:135], v[166:167], off
	global_load_dwordx4 v[128:131], v[166:167], off offset:256
	v_add_co_u32_e32 v182, vcc, 0x10000, v180
	s_nop 1
	v_addc_co_u32_e32 v183, vcc, 0, v181, vcc
	global_load_dwordx4 v[190:193], v[182:183], off
	global_load_dwordx4 v[194:197], v[182:183], off offset:256
	v_add_co_u32_e32 v182, vcc, 0x18000, v180
	s_nop 1
	v_addc_co_u32_e32 v183, vcc, 0, v181, vcc
	global_load_dwordx4 v[216:219], v[182:183], off
	global_load_dwordx4 v[220:223], v[182:183], off offset:256
	v_add_co_u32_e32 v182, vcc, 0x40000, v180
	s_nop 1
	v_addc_co_u32_e32 v183, vcc, 0, v181, vcc
	global_load_dwordx4 v[224:227], v[182:183], off
	global_load_dwordx4 v[228:231], v[182:183], off offset:256
	v_add_co_u32_e32 v182, vcc, 0x48000, v180
	s_nop 1
	v_addc_co_u32_e32 v183, vcc, 0, v181, vcc
	global_load_dwordx4 v[232:235], v[182:183], off
	global_load_dwordx4 v[236:239], v[182:183], off offset:256
	v_add_co_u32_e32 v182, vcc, 0x50000, v180
	s_nop 1
	v_addc_co_u32_e32 v183, vcc, 0, v181, vcc
	global_load_dwordx4 v[240:243], v[182:183], off
	global_load_dwordx4 v[244:247], v[182:183], off offset:256
	v_and_b32_e32 v171, 64, v203
	v_xor_b32_e32 v170, 16, v203
	v_add_u32_e32 v171, 64, v171
	v_xor_b32_e32 v182, 32, v203
	v_cmp_lt_i32_e32 vcc, v170, v171
	s_lshl_b32 s16, s56, 2
	s_ashr_i32 s17, s16, 31
	v_cndmask_b32_e32 v170, v203, v170, vcc
	v_cmp_lt_i32_e32 vcc, v182, v171
	v_lshlrev_b32_e32 v171, 2, v170
	s_waitcnt vmcnt(12)
	v_and_b32_e32 v183, 0xffff0000, v172
	v_cndmask_b32_e32 v182, v203, v182, vcc
	v_lshlrev_b32_e32 v170, 2, v182
	v_lshlrev_b32_e32 v182, 16, v172
	v_lshlrev_b32_e32 v172, 16, v173
	v_and_b32_e32 v173, 0xffff0000, v173
	v_lshlrev_b32_e32 v184, 16, v174
	v_and_b32_e32 v185, 0xffff0000, v174
	v_lshlrev_b32_e32 v174, 16, v175
	v_and_b32_e32 v175, 0xffff0000, v175
	v_lshlrev_b32_e32 v186, 16, v176
	v_and_b32_e32 v187, 0xffff0000, v176
	v_lshlrev_b32_e32 v176, 16, v177
	v_and_b32_e32 v177, 0xffff0000, v177
	v_lshlrev_b32_e32 v188, 16, v178
	v_and_b32_e32 v189, 0xffff0000, v178
	v_lshlrev_b32_e32 v178, 16, v179
	v_and_b32_e32 v179, 0xffff0000, v179
	v_pk_fma_f32 v[126:127], v[126:127], 0.5, v[172:173] op_sel_hi:[1,0,1]
	v_pk_fma_f32 v[124:125], v[124:125], 0.5, v[182:183] op_sel_hi:[1,0,1]
	v_pk_fma_f32 v[122:123], v[122:123], 0.5, v[174:175] op_sel_hi:[1,0,1]
	v_pk_fma_f32 v[120:121], v[120:121], 0.5, v[184:185] op_sel_hi:[1,0,1]
	v_pk_fma_f32 v[118:119], v[118:119], 0.5, v[176:177] op_sel_hi:[1,0,1]
	v_pk_fma_f32 v[116:117], v[116:117], 0.5, v[186:187] op_sel_hi:[1,0,1]
	v_pk_fma_f32 v[172:173], v[114:115], 0.5, v[178:179] op_sel_hi:[1,0,1]
	v_pk_fma_f32 v[174:175], v[112:113], 0.5, v[188:189] op_sel_hi:[1,0,1]
	v_cvt_pk_bf16_f32 v112, v124, v125
	v_cvt_pk_bf16_f32 v113, v126, v127
	v_mul_f32_e32 v114, v125, v125
	v_mul_f32_e32 v115, v127, v127
	v_mul_f32_e32 v125, v121, v121
	v_mul_f32_e32 v127, v123, v123
	v_mul_f32_e32 v176, v117, v117
	v_mul_f32_e32 v177, v119, v119
	v_mul_f32_e32 v178, v175, v175
	v_mul_f32_e32 v179, v173, v173
	v_fmac_f32_e32 v114, v124, v124
	v_fmac_f32_e32 v115, v126, v126
	v_fmac_f32_e32 v125, v120, v120
	v_fmac_f32_e32 v127, v122, v122
	v_fmac_f32_e32 v176, v116, v116
	v_fmac_f32_e32 v177, v118, v118
	v_fmac_f32_e32 v178, v174, v174
	v_fmac_f32_e32 v179, v172, v172
	v_add_f32_e32 v114, v114, v115
	v_add_f32_e32 v115, v125, v127
	v_add_f32_e32 v124, v176, v177
	v_add_f32_e32 v125, v178, v179
	v_add_f32_e32 v114, v114, v115
	v_add_f32_e32 v115, v124, v125
	v_add_f32_e32 v124, v114, v115
	ds_bpermute_b32 v125, v171, v124
	v_cvt_pk_bf16_f32 v114, v120, v121
	v_cvt_pk_bf16_f32 v115, v122, v123
	global_store_dwordx4 v[180:181], v[112:115], off
	s_waitcnt lgkmcnt(0)
	s_nop 0
	v_add_f32_e32 v112, v124, v125
	ds_bpermute_b32 v113, v170, v112
	v_cvt_pk_bf16_f32 v114, v116, v117
	v_cvt_pk_bf16_f32 v115, v118, v119
	v_cvt_pk_bf16_f32 v116, v174, v175
	v_cvt_pk_bf16_f32 v117, v172, v173
	global_store_dwordx4 v[180:181], v[114:117], off offset:256
	s_and_saveexec_b64 s[28:29], s[36:37]
	s_cbranch_execz .LBB0_275
	v_lshlrev_b64 v[114:115], 6, v[162:163]
	v_lshl_add_u64 v[114:115], s[10:11], 0, v[114:115]
	v_lshl_add_u64 v[114:115], s[16:17], 2, v[114:115]
	s_lshl_b32 s40, s48, 2
	s_mov_b32 s41, s5
	v_lshl_add_u64 v[114:115], v[114:115], 0, s[40:41]
	s_waitcnt lgkmcnt(0)
	v_add_f32_e32 v112, v112, v113
	global_store_dword v[114:115], v112, off
; __device__ __forceinline__ u32x2 pack4(f32x4 v) { u32x2 w; w.x = cvt_pk_bf16(v[0], v[1]); w.y = cvt_pk_bf16(v[2], v[3]); return w; }
;     __device__ __forceinline__ void gload(Grp& h, size_t off) const {
;         if constexpr (F32IN) { h.f[0] = *(const f32x4*)(hin + off); h.f[1] = *(const f32x4*)(hin + off + 4); h.f[2] = *(const f32x4*)(hin + off + HALF); h.f[3] = *(const f32x4*)(hin + off + HALF + 4); }
;         else { const u32x4 a = *(const u32x4*)(xa + off), b = *(const u32x4*)(xa + off + HALF); h.f[0] = __builtin_bit_cast(f32x4, a); h.f[2] = __builtin_bit_cast(f32x4, b); }
;     }
;     __device__ __forceinline__ void unpack(const Grp& h, int bj, f32x4& v0, f32x4& v1) const {
;         if constexpr (F32IN) { v0 = h.f[2 * bj]; v1 = h.f[2 * bj + 1]; }
;         else { const u32x4 w = __builtin_bit_cast(u32x4, h.f[2 * bj]);
;             v0[0] = __uint_as_float(w.x << 16); v0[1] = __uint_as_float(w.x & 0xffff0000u); v0[2] = __uint_as_float(w.y << 16); v0[3] = __uint_as_float(w.y & 0xffff0000u);
;             v1[0] = __uint_as_float(w.z << 16); v1[1] = __uint_as_float(w.z & 0xffff0000u); v1[2] = __uint_as_float(w.w << 16); v1[3] = __uint_as_float(w.w & 0xffff0000u); }
;     }
;     __device__ __forceinline__ void operator()(const f32x4 (&acc)[2][2][4][2], const Unit& u, int wr, int wc, int fr, int fq) const {
;         Grp h[2];
;         gload(h[0], goff(u, 0, wr, wc, fr, fq));
; #pragma unroll
;         for (int g = 0; g < 8; ++g) {
;             const int ai = g >> 2, m = g & 3; const size_t off = goff(u, g, wr, wc, fr, fq);
;             if (g < 7) gload(h[(g + 1) & 1], goff(u, g + 1, wr, wc, fr, fq));
;             float sq = 0.f;
; #pragma unroll
;             for (int bj = 0; bj < 2; ++bj) { const size_t o = off + bj * HALF; f32x4 h0, h1; unpack(h[g & 1], bj, h0, h1);
;                 h0 = h0 + acc[ai][bj][m][0] * alpha; h1 = h1 + acc[ai][bj][m][1] * alpha;
;                 const u32x2 p0 = pack4(h0), p1 = pack4(h1); u32x4 w; w.x = p0.x; w.y = p0.y; w.z = p1.x; w.w = p1.y; *(u32x4*)(xa + o) = w;
;                 sq += ((h0[0] * h0[0] + h0[1] * h0[1]) + (h0[2] * h0[2] + h0[3] * h0[3])) + ((h1[0] * h1[0] + h1[1] * h1[1]) + (h1[2] * h1[2] + h1[3] * h1[3])); }
;             sq += __shfl_xor(sq, 16); sq += __shfl_xor(sq, 32);
;             if (fq == 0) ssout[(size_t)(u.pm * BM + ai * HALF + wr * 64 + m * 16 + fr) * 16 + u.pn * 4 + wc] = sq;
.LBB0_275:
	s_or_b64 exec, exec, s[28:29]
	v_or_b32_e32 v120, 32, v162
	v_ashrrev_i32_e32 v121, 31, v120
	s_waitcnt lgkmcnt(0)
	v_lshlrev_b64 v[112:113], 11, v[120:121]
	v_lshl_add_u64 v[112:113], s[22:23], 0, v[112:113]
	v_lshl_add_u64 v[112:113], s[18:19], 1, v[112:113]
	v_lshl_add_u64 v[112:113], v[112:113], 0, s[4:5]
	v_lshl_add_u64 v[122:123], v[112:113], 0, v[144:145]
	s_waitcnt vmcnt(12)
	v_lshlrev_b32_e32 v124, 16, v132
	v_and_b32_e32 v125, 0xffff0000, v132
	v_lshlrev_b32_e32 v126, 16, v133
	v_and_b32_e32 v127, 0xffff0000, v133
	v_lshlrev_b32_e32 v132, 16, v134
	v_and_b32_e32 v133, 0xffff0000, v134
	v_lshlrev_b32_e32 v134, 16, v135
	v_and_b32_e32 v135, 0xffff0000, v135
	v_pk_fma_f32 v[108:109], v[108:109], 0.5, v[124:125] op_sel_hi:[1,0,1]
	v_pk_fma_f32 v[110:111], v[110:111], 0.5, v[126:127] op_sel_hi:[1,0,1]
	v_pk_fma_f32 v[124:125], v[106:107], 0.5, v[134:135] op_sel_hi:[1,0,1]
	v_pk_fma_f32 v[106:107], v[104:105], 0.5, v[132:133] op_sel_hi:[1,0,1]
	v_cvt_pk_bf16_f32 v104, v108, v109
	v_mul_f32_e32 v109, v109, v109
	v_fmac_f32_e32 v109, v108, v108
	v_mul_f32_e32 v108, v111, v111
	v_fmac_f32_e32 v108, v110, v110
	v_cvt_pk_bf16_f32 v105, v110, v111
	v_add_f32_e32 v108, v109, v108
	v_mul_f32_e32 v109, v107, v107
	v_mul_f32_e32 v110, v125, v125
	v_fmac_f32_e32 v109, v106, v106
	v_fmac_f32_e32 v110, v124, v124
	v_add_f32_e32 v109, v109, v110
	v_add_f32_e32 v132, v108, v109
	v_lshlrev_b32_e32 v108, 16, v128
	v_and_b32_e32 v109, 0xffff0000, v128
	v_lshlrev_b32_e32 v110, 16, v129
	v_and_b32_e32 v111, 0xffff0000, v129
	v_lshlrev_b32_e32 v126, 16, v130
	v_and_b32_e32 v127, 0xffff0000, v130
	v_pk_fma_f32 v[102:103], v[102:103], 0.5, v[110:111] op_sel_hi:[1,0,1]
	v_pk_fma_f32 v[100:101], v[100:101], 0.5, v[108:109] op_sel_hi:[1,0,1]
	v_lshlrev_b32_e32 v128, 16, v131
	v_and_b32_e32 v129, 0xffff0000, v131
	v_pk_fma_f32 v[110:111], v[96:97], 0.5, v[126:127] op_sel_hi:[1,0,1]
	v_mul_f32_e32 v96, v101, v101
	v_mul_f32_e32 v97, v103, v103
	v_pk_fma_f32 v[108:109], v[98:99], 0.5, v[128:129] op_sel_hi:[1,0,1]
	v_fmac_f32_e32 v96, v100, v100
	v_fmac_f32_e32 v97, v102, v102
	v_add_f32_e32 v96, v96, v97
	v_mul_f32_e32 v97, v111, v111
	v_mul_f32_e32 v98, v109, v109
	v_fmac_f32_e32 v97, v110, v110
	v_fmac_f32_e32 v98, v108, v108
	v_add_f32_e32 v97, v97, v98
	v_add_f32_e32 v96, v96, v97
	v_add_f32_e32 v96, v132, v96
	ds_bpermute_b32 v97, v171, v96
	v_cvt_pk_bf16_f32 v106, v106, v107
	v_cvt_pk_bf16_f32 v107, v124, v125
	v_cvt_pk_bf16_f32 v98, v100, v101
	v_cvt_pk_bf16_f32 v99, v102, v103
	s_waitcnt lgkmcnt(0)
	v_add_f32_e32 v96, v96, v97
	ds_bpermute_b32 v97, v170, v96
	v_cvt_pk_bf16_f32 v100, v110, v111
	v_cvt_pk_bf16_f32 v101, v108, v109
	global_store_dwordx4 v[166:167], v[104:107], off
	global_store_dwordx4 v[166:167], v[98:101], off offset:256
	s_and_saveexec_b64 s[28:29], s[36:37]
	s_cbranch_execz .LBB0_277
	v_lshlrev_b64 v[98:99], 6, v[164:165]
	v_lshl_add_u64 v[98:99], s[10:11], 0, v[98:99]
	v_lshl_add_u64 v[98:99], s[16:17], 2, v[98:99]
	s_lshl_b32 s40, s48, 2
	s_mov_b32 s41, s5
	v_lshl_add_u64 v[98:99], v[98:99], 0, s[40:41]
	s_waitcnt lgkmcnt(0)
	v_add_f32_e32 v96, v96, v97
	global_store_dword v[98:99], v96, off
.LBB0_277:
	s_or_b64 exec, exec, s[28:29]
	v_or_b32_e32 v104, 48, v162
	v_ashrrev_i32_e32 v105, 31, v104
	s_waitcnt lgkmcnt(0)
	v_lshlrev_b64 v[96:97], 11, v[104:105]
	v_lshl_add_u64 v[96:97], s[22:23], 0, v[96:97]
	v_lshl_add_u64 v[96:97], s[18:19], 1, v[96:97]
	v_lshl_add_u64 v[96:97], v[96:97], 0, s[4:5]
	v_lshl_add_u64 v[106:107], v[96:97], 0, v[144:145]
	s_waitcnt vmcnt(12)
	s_waitcnt vmcnt(12)
	v_lshlrev_b32_e32 v108, 16, v190
	v_and_b32_e32 v109, 0xffff0000, v190
	v_lshlrev_b32_e32 v110, 16, v191
	v_and_b32_e32 v111, 0xffff0000, v191
	v_lshlrev_b32_e32 v116, 16, v192
	v_and_b32_e32 v117, 0xffff0000, v192
	v_lshlrev_b32_e32 v118, 16, v193
	v_and_b32_e32 v119, 0xffff0000, v193
	v_pk_fma_f32 v[92:93], v[92:93], 0.5, v[108:109] op_sel_hi:[1,0,1]
	v_pk_fma_f32 v[94:95], v[94:95], 0.5, v[110:111] op_sel_hi:[1,0,1]
	v_pk_fma_f32 v[108:109], v[90:91], 0.5, v[118:119] op_sel_hi:[1,0,1]
	v_pk_fma_f32 v[90:91], v[88:89], 0.5, v[116:117] op_sel_hi:[1,0,1]
	v_cvt_pk_bf16_f32 v88, v92, v93
	v_mul_f32_e32 v93, v93, v93
	v_fmac_f32_e32 v93, v92, v92
	v_mul_f32_e32 v92, v95, v95
	v_fmac_f32_e32 v92, v94, v94
	v_cvt_pk_bf16_f32 v89, v94, v95
	v_add_f32_e32 v92, v93, v92
	v_mul_f32_e32 v93, v91, v91
	v_mul_f32_e32 v94, v109, v109
	v_fmac_f32_e32 v93, v90, v90
	v_fmac_f32_e32 v94, v108, v108
	v_add_f32_e32 v93, v93, v94
	v_add_f32_e32 v116, v92, v93
	s_waitcnt vmcnt(12)
	v_lshlrev_b32_e32 v92, 16, v194
	v_and_b32_e32 v93, 0xffff0000, v194
	v_lshlrev_b32_e32 v94, 16, v195
	v_and_b32_e32 v95, 0xffff0000, v195
	v_lshlrev_b32_e32 v110, 16, v196
	v_and_b32_e32 v111, 0xffff0000, v196
	v_pk_fma_f32 v[86:87], v[86:87], 0.5, v[94:95] op_sel_hi:[1,0,1]
	v_pk_fma_f32 v[84:85], v[84:85], 0.5, v[92:93] op_sel_hi:[1,0,1]
	v_lshlrev_b32_e32 v112, 16, v197
	v_and_b32_e32 v113, 0xffff0000, v197
	v_pk_fma_f32 v[94:95], v[80:81], 0.5, v[110:111] op_sel_hi:[1,0,1]
	v_mul_f32_e32 v80, v85, v85
	v_mul_f32_e32 v81, v87, v87
	v_pk_fma_f32 v[92:93], v[82:83], 0.5, v[112:113] op_sel_hi:[1,0,1]
	v_fmac_f32_e32 v80, v84, v84
	v_fmac_f32_e32 v81, v86, v86
	v_add_f32_e32 v80, v80, v81
	v_mul_f32_e32 v81, v95, v95
	v_mul_f32_e32 v82, v93, v93
	v_fmac_f32_e32 v81, v94, v94
	v_fmac_f32_e32 v82, v92, v92
	v_add_f32_e32 v81, v81, v82
	v_add_f32_e32 v80, v80, v81
	v_add_f32_e32 v80, v116, v80
	ds_bpermute_b32 v81, v171, v80
	v_cvt_pk_bf16_f32 v90, v90, v91
	v_cvt_pk_bf16_f32 v91, v108, v109
	v_cvt_pk_bf16_f32 v82, v84, v85
	v_cvt_pk_bf16_f32 v83, v86, v87
	s_waitcnt lgkmcnt(0)
	v_add_f32_e32 v80, v80, v81
	ds_bpermute_b32 v81, v170, v80
	v_cvt_pk_bf16_f32 v84, v94, v95
	v_cvt_pk_bf16_f32 v85, v92, v93
	global_store_dwordx4 v[122:123], v[88:91], off
	global_store_dwordx4 v[122:123], v[82:85], off offset:256
	s_and_saveexec_b64 s[28:29], s[36:37]
	s_cbranch_execz .LBB0_279
	v_lshlrev_b64 v[82:83], 6, v[120:121]
	v_lshl_add_u64 v[82:83], s[10:11], 0, v[82:83]
	v_lshl_add_u64 v[82:83], s[16:17], 2, v[82:83]
	s_lshl_b32 s40, s48, 2
	s_mov_b32 s41, s5
	v_lshl_add_u64 v[82:83], v[82:83], 0, s[40:41]
	s_waitcnt lgkmcnt(0)
	v_add_f32_e32 v80, v80, v81
	global_store_dword v[82:83], v80, off
; __device__ __forceinline__ u32x2 pack4(f32x4 v) { u32x2 w; w.x = cvt_pk_bf16(v[0], v[1]); w.y = cvt_pk_bf16(v[2], v[3]); return w; }
;     __device__ __forceinline__ void gload(Grp& h, size_t off) const {
;         if constexpr (F32IN) { h.f[0] = *(const f32x4*)(hin + off); h.f[1] = *(const f32x4*)(hin + off + 4); h.f[2] = *(const f32x4*)(hin + off + HALF); h.f[3] = *(const f32x4*)(hin + off + HALF + 4); }
;         else { const u32x4 a = *(const u32x4*)(xa + off), b = *(const u32x4*)(xa + off + HALF); h.f[0] = __builtin_bit_cast(f32x4, a); h.f[2] = __builtin_bit_cast(f32x4, b); }
;     }
;     __device__ __forceinline__ void unpack(const Grp& h, int bj, f32x4& v0, f32x4& v1) const {
;         if constexpr (F32IN) { v0 = h.f[2 * bj]; v1 = h.f[2 * bj + 1]; }
;         else { const u32x4 w = __builtin_bit_cast(u32x4, h.f[2 * bj]);
;             v0[0] = __uint_as_float(w.x << 16); v0[1] = __uint_as_float(w.x & 0xffff0000u); v0[2] = __uint_as_float(w.y << 16); v0[3] = __uint_as_float(w.y & 0xffff0000u);
;             v1[0] = __uint_as_float(w.z << 16); v1[1] = __uint_as_float(w.z & 0xffff0000u); v1[2] = __uint_as_float(w.w << 16); v1[3] = __uint_as_float(w.w & 0xffff0000u); }
;     }
;     __device__ __forceinline__ void operator()(const f32x4 (&acc)[2][2][4][2], const Unit& u, int wr, int wc, int fr, int fq) const {
;         Grp h[2];
;         gload(h[0], goff(u, 0, wr, wc, fr, fq));
; #pragma unroll
;         for (int g = 0; g < 8; ++g) {
;             const int ai = g >> 2, m = g & 3; const size_t off = goff(u, g, wr, wc, fr, fq);
;             if (g < 7) gload(h[(g + 1) & 1], goff(u, g + 1, wr, wc, fr, fq));
;             float sq = 0.f;
; #pragma unroll
;             for (int bj = 0; bj < 2; ++bj) { const size_t o = off + bj * HALF; f32x4 h0, h1; unpack(h[g & 1], bj, h0, h1);
;                 h0 = h0 + acc[ai][bj][m][0] * alpha; h1 = h1 + acc[ai][bj][m][1] * alpha;
;                 const u32x2 p0 = pack4(h0), p1 = pack4(h1); u32x4 w; w.x = p0.x; w.y = p0.y; w.z = p1.x; w.w = p1.y; *(u32x4*)(xa + o) = w;
;                 sq += ((h0[0] * h0[0] + h0[1] * h0[1]) + (h0[2] * h0[2] + h0[3] * h0[3])) + ((h1[0] * h1[0] + h1[1] * h1[1]) + (h1[2] * h1[2] + h1[3] * h1[3])); }
;             sq += __shfl_xor(sq, 16); sq += __shfl_xor(sq, 32);
;             if (fq == 0) ssout[(size_t)(u.pm * BM + ai * HALF + wr * 64 + m * 16 + fr) * 16 + u.pn * 4 + wc] = sq;
.LBB0_279:
	s_or_b64 exec, exec, s[28:29]
	v_add_u32_e32 v88, 0x80, v162
	v_ashrrev_i32_e32 v89, 31, v88
	s_waitcnt lgkmcnt(0)
	v_lshlrev_b64 v[80:81], 11, v[88:89]
	v_lshl_add_u64 v[80:81], s[22:23], 0, v[80:81]
	v_lshl_add_u64 v[80:81], s[18:19], 1, v[80:81]
	v_lshl_add_u64 v[80:81], v[80:81], 0, s[4:5]
	v_lshl_add_u64 v[90:91], v[80:81], 0, v[144:145]
	s_waitcnt vmcnt(12)
	s_waitcnt vmcnt(12)
	v_lshlrev_b32_e32 v92, 16, v216
	v_and_b32_e32 v93, 0xffff0000, v216
	v_lshlrev_b32_e32 v94, 16, v217
	v_and_b32_e32 v95, 0xffff0000, v217
	v_lshlrev_b32_e32 v100, 16, v218
	v_and_b32_e32 v101, 0xffff0000, v218
	v_lshlrev_b32_e32 v102, 16, v219
	v_and_b32_e32 v103, 0xffff0000, v219
	v_pk_fma_f32 v[76:77], v[76:77], 0.5, v[92:93] op_sel_hi:[1,0,1]
	v_pk_fma_f32 v[78:79], v[78:79], 0.5, v[94:95] op_sel_hi:[1,0,1]
	v_pk_fma_f32 v[92:93], v[74:75], 0.5, v[102:103] op_sel_hi:[1,0,1]
	v_pk_fma_f32 v[74:75], v[72:73], 0.5, v[100:101] op_sel_hi:[1,0,1]
	v_cvt_pk_bf16_f32 v72, v76, v77
	v_mul_f32_e32 v77, v77, v77
	v_fmac_f32_e32 v77, v76, v76
	v_mul_f32_e32 v76, v79, v79
	v_fmac_f32_e32 v76, v78, v78
	v_cvt_pk_bf16_f32 v73, v78, v79
	v_add_f32_e32 v76, v77, v76
	v_mul_f32_e32 v77, v75, v75
	v_mul_f32_e32 v78, v93, v93
	v_fmac_f32_e32 v77, v74, v74
	v_fmac_f32_e32 v78, v92, v92
	v_add_f32_e32 v77, v77, v78
	v_add_f32_e32 v100, v76, v77
	s_waitcnt vmcnt(12)
	v_lshlrev_b32_e32 v76, 16, v220
	v_and_b32_e32 v77, 0xffff0000, v220
	v_lshlrev_b32_e32 v78, 16, v221
	v_and_b32_e32 v79, 0xffff0000, v221
	v_lshlrev_b32_e32 v94, 16, v222
	v_and_b32_e32 v95, 0xffff0000, v222
	v_pk_fma_f32 v[70:71], v[70:71], 0.5, v[78:79] op_sel_hi:[1,0,1]
	v_pk_fma_f32 v[68:69], v[68:69], 0.5, v[76:77] op_sel_hi:[1,0,1]
	v_lshlrev_b32_e32 v96, 16, v223
	v_and_b32_e32 v97, 0xffff0000, v223
	v_pk_fma_f32 v[78:79], v[64:65], 0.5, v[94:95] op_sel_hi:[1,0,1]
	v_mul_f32_e32 v64, v69, v69
	v_mul_f32_e32 v65, v71, v71
	v_pk_fma_f32 v[76:77], v[66:67], 0.5, v[96:97] op_sel_hi:[1,0,1]
	v_fmac_f32_e32 v64, v68, v68
	v_fmac_f32_e32 v65, v70, v70
	v_add_f32_e32 v64, v64, v65
	v_mul_f32_e32 v65, v79, v79
	v_mul_f32_e32 v66, v77, v77
	v_fmac_f32_e32 v65, v78, v78
	v_fmac_f32_e32 v66, v76, v76
	v_add_f32_e32 v65, v65, v66
	v_add_f32_e32 v64, v64, v65
	v_add_f32_e32 v64, v100, v64
	ds_bpermute_b32 v65, v171, v64
	v_cvt_pk_bf16_f32 v74, v74, v75
	v_cvt_pk_bf16_f32 v75, v92, v93
	v_cvt_pk_bf16_f32 v66, v68, v69
	v_cvt_pk_bf16_f32 v67, v70, v71
	s_waitcnt lgkmcnt(0)
	v_add_f32_e32 v64, v64, v65
	ds_bpermute_b32 v65, v170, v64
	v_cvt_pk_bf16_f32 v68, v78, v79
	v_cvt_pk_bf16_f32 v69, v76, v77
	global_store_dwordx4 v[106:107], v[72:75], off
	global_store_dwordx4 v[106:107], v[66:69], off offset:256
	s_and_saveexec_b64 s[28:29], s[36:37]
	s_cbranch_execz .LBB0_281
	v_lshlrev_b64 v[66:67], 6, v[104:105]
	v_lshl_add_u64 v[66:67], s[10:11], 0, v[66:67]
	v_lshl_add_u64 v[66:67], s[16:17], 2, v[66:67]
	s_lshl_b32 s40, s48, 2
	s_mov_b32 s41, s5
	v_lshl_add_u64 v[66:67], v[66:67], 0, s[40:41]
	s_waitcnt lgkmcnt(0)
	v_add_f32_e32 v64, v64, v65
	global_store_dword v[66:67], v64, off
.LBB0_281:
	s_or_b64 exec, exec, s[28:29]
	v_or_b32_e32 v72, 16, v88
	v_ashrrev_i32_e32 v73, 31, v72
	s_waitcnt lgkmcnt(0)
	v_lshlrev_b64 v[64:65], 11, v[72:73]
	v_lshl_add_u64 v[64:65], s[22:23], 0, v[64:65]
	v_lshl_add_u64 v[64:65], s[18:19], 1, v[64:65]
	v_lshl_add_u64 v[64:65], v[64:65], 0, s[4:5]
	v_lshl_add_u64 v[74:75], v[64:65], 0, v[144:145]
	s_waitcnt vmcnt(12)
	s_waitcnt vmcnt(12)
	v_lshlrev_b32_e32 v76, 16, v224
	v_and_b32_e32 v77, 0xffff0000, v224
	v_lshlrev_b32_e32 v78, 16, v225
	v_and_b32_e32 v79, 0xffff0000, v225
	v_lshlrev_b32_e32 v84, 16, v226
	v_and_b32_e32 v85, 0xffff0000, v226
	v_lshlrev_b32_e32 v86, 16, v227
	v_and_b32_e32 v87, 0xffff0000, v227
	v_pk_fma_f32 v[60:61], v[60:61], 0.5, v[76:77] op_sel_hi:[1,0,1]
	v_pk_fma_f32 v[62:63], v[62:63], 0.5, v[78:79] op_sel_hi:[1,0,1]
	v_pk_fma_f32 v[76:77], v[58:59], 0.5, v[86:87] op_sel_hi:[1,0,1]
	v_pk_fma_f32 v[58:59], v[56:57], 0.5, v[84:85] op_sel_hi:[1,0,1]
	v_cvt_pk_bf16_f32 v56, v60, v61
	v_mul_f32_e32 v61, v61, v61
	v_fmac_f32_e32 v61, v60, v60
	v_mul_f32_e32 v60, v63, v63
	v_fmac_f32_e32 v60, v62, v62
	v_cvt_pk_bf16_f32 v57, v62, v63
	v_add_f32_e32 v60, v61, v60
	v_mul_f32_e32 v61, v59, v59
	v_mul_f32_e32 v62, v77, v77
	v_fmac_f32_e32 v61, v58, v58
	v_fmac_f32_e32 v62, v76, v76
	v_add_f32_e32 v61, v61, v62
	v_add_f32_e32 v84, v60, v61
	s_waitcnt vmcnt(12)
	v_lshlrev_b32_e32 v60, 16, v228
	v_and_b32_e32 v61, 0xffff0000, v228
	v_lshlrev_b32_e32 v62, 16, v229
	v_and_b32_e32 v63, 0xffff0000, v229
	v_lshlrev_b32_e32 v78, 16, v230
	v_and_b32_e32 v79, 0xffff0000, v230
	v_pk_fma_f32 v[54:55], v[54:55], 0.5, v[62:63] op_sel_hi:[1,0,1]
	v_pk_fma_f32 v[52:53], v[52:53], 0.5, v[60:61] op_sel_hi:[1,0,1]
	v_lshlrev_b32_e32 v80, 16, v231
	v_and_b32_e32 v81, 0xffff0000, v231
	v_pk_fma_f32 v[62:63], v[48:49], 0.5, v[78:79] op_sel_hi:[1,0,1]
	v_mul_f32_e32 v48, v53, v53
	v_mul_f32_e32 v49, v55, v55
	v_pk_fma_f32 v[60:61], v[50:51], 0.5, v[80:81] op_sel_hi:[1,0,1]
	v_fmac_f32_e32 v48, v52, v52
	v_fmac_f32_e32 v49, v54, v54
	v_add_f32_e32 v48, v48, v49
	v_mul_f32_e32 v49, v63, v63
	v_mul_f32_e32 v50, v61, v61
	v_fmac_f32_e32 v49, v62, v62
	v_fmac_f32_e32 v50, v60, v60
	v_add_f32_e32 v49, v49, v50
	v_add_f32_e32 v48, v48, v49
	v_add_f32_e32 v48, v84, v48
	ds_bpermute_b32 v49, v171, v48
	v_cvt_pk_bf16_f32 v58, v58, v59
	v_cvt_pk_bf16_f32 v59, v76, v77
	v_cvt_pk_bf16_f32 v50, v52, v53
	v_cvt_pk_bf16_f32 v51, v54, v55
	s_waitcnt lgkmcnt(0)
	v_add_f32_e32 v48, v48, v49
	ds_bpermute_b32 v49, v170, v48
	v_cvt_pk_bf16_f32 v52, v62, v63
	v_cvt_pk_bf16_f32 v53, v60, v61
	global_store_dwordx4 v[90:91], v[56:59], off
	global_store_dwordx4 v[90:91], v[50:53], off offset:256
	s_and_saveexec_b64 s[28:29], s[36:37]
	s_cbranch_execz .LBB0_283
	v_lshlrev_b64 v[50:51], 6, v[88:89]
	v_lshl_add_u64 v[50:51], s[10:11], 0, v[50:51]
	v_lshl_add_u64 v[50:51], s[16:17], 2, v[50:51]
	s_lshl_b32 s40, s48, 2
	s_mov_b32 s41, s5
	v_lshl_add_u64 v[50:51], v[50:51], 0, s[40:41]
	s_waitcnt lgkmcnt(0)
	v_add_f32_e32 v48, v48, v49
	global_store_dword v[50:51], v48, off
; __device__ __forceinline__ u32x2 pack4(f32x4 v) { u32x2 w; w.x = cvt_pk_bf16(v[0], v[1]); w.y = cvt_pk_bf16(v[2], v[3]); return w; }
;     __device__ __forceinline__ void gload(Grp& h, size_t off) const {
;         if constexpr (F32IN) { h.f[0] = *(const f32x4*)(hin + off); h.f[1] = *(const f32x4*)(hin + off + 4); h.f[2] = *(const f32x4*)(hin + off + HALF); h.f[3] = *(const f32x4*)(hin + off + HALF + 4); }
;         else { const u32x4 a = *(const u32x4*)(xa + off), b = *(const u32x4*)(xa + off + HALF); h.f[0] = __builtin_bit_cast(f32x4, a); h.f[2] = __builtin_bit_cast(f32x4, b); }
;     }
;     __device__ __forceinline__ void unpack(const Grp& h, int bj, f32x4& v0, f32x4& v1) const {
;         if constexpr (F32IN) { v0 = h.f[2 * bj]; v1 = h.f[2 * bj + 1]; }
;         else { const u32x4 w = __builtin_bit_cast(u32x4, h.f[2 * bj]);
;             v0[0] = __uint_as_float(w.x << 16); v0[1] = __uint_as_float(w.x & 0xffff0000u); v0[2] = __uint_as_float(w.y << 16); v0[3] = __uint_as_float(w.y & 0xffff0000u);
;             v1[0] = __uint_as_float(w.z << 16); v1[1] = __uint_as_float(w.z & 0xffff0000u); v1[2] = __uint_as_float(w.w << 16); v1[3] = __uint_as_float(w.w & 0xffff0000u); }
;     }
;     __device__ __forceinline__ void operator()(const f32x4 (&acc)[2][2][4][2], const Unit& u, int wr, int wc, int fr, int fq) const {
;         Grp h[2];
;         gload(h[0], goff(u, 0, wr, wc, fr, fq));
; #pragma unroll
;         for (int g = 0; g < 8; ++g) {
;             const int ai = g >> 2, m = g & 3; const size_t off = goff(u, g, wr, wc, fr, fq);
;             if (g < 7) gload(h[(g + 1) & 1], goff(u, g + 1, wr, wc, fr, fq));
;             float sq = 0.f;
; #pragma unroll
;             for (int bj = 0; bj < 2; ++bj) { const size_t o = off + bj * HALF; f32x4 h0, h1; unpack(h[g & 1], bj, h0, h1);
;                 h0 = h0 + acc[ai][bj][m][0] * alpha; h1 = h1 + acc[ai][bj][m][1] * alpha;
;                 const u32x2 p0 = pack4(h0), p1 = pack4(h1); u32x4 w; w.x = p0.x; w.y = p0.y; w.z = p1.x; w.w = p1.y; *(u32x4*)(xa + o) = w;
;                 sq += ((h0[0] * h0[0] + h0[1] * h0[1]) + (h0[2] * h0[2] + h0[3] * h0[3])) + ((h1[0] * h1[0] + h1[1] * h1[1]) + (h1[2] * h1[2] + h1[3] * h1[3])); }
;             sq += __shfl_xor(sq, 16); sq += __shfl_xor(sq, 32);
;             if (fq == 0) ssout[(size_t)(u.pm * BM + ai * HALF + wr * 64 + m * 16 + fr) * 16 + u.pn * 4 + wc] = sq;
.LBB0_283:
	s_or_b64 exec, exec, s[28:29]
	v_or_b32_e32 v56, 32, v88
	v_ashrrev_i32_e32 v57, 31, v56
	s_waitcnt lgkmcnt(0)
	v_lshlrev_b64 v[48:49], 11, v[56:57]
	v_lshl_add_u64 v[48:49], s[22:23], 0, v[48:49]
	v_lshl_add_u64 v[48:49], s[18:19], 1, v[48:49]
	v_lshl_add_u64 v[48:49], v[48:49], 0, s[4:5]
	v_lshl_add_u64 v[58:59], v[48:49], 0, v[144:145]
	s_waitcnt vmcnt(12)
	s_waitcnt vmcnt(12)
	v_lshlrev_b32_e32 v60, 16, v232
	v_and_b32_e32 v61, 0xffff0000, v232
	v_lshlrev_b32_e32 v62, 16, v233
	v_and_b32_e32 v63, 0xffff0000, v233
	v_lshlrev_b32_e32 v68, 16, v234
	v_and_b32_e32 v69, 0xffff0000, v234
	v_lshlrev_b32_e32 v70, 16, v235
	v_and_b32_e32 v71, 0xffff0000, v235
	v_pk_fma_f32 v[44:45], v[44:45], 0.5, v[60:61] op_sel_hi:[1,0,1]
	v_pk_fma_f32 v[46:47], v[46:47], 0.5, v[62:63] op_sel_hi:[1,0,1]
	v_pk_fma_f32 v[60:61], v[42:43], 0.5, v[70:71] op_sel_hi:[1,0,1]
	v_pk_fma_f32 v[42:43], v[40:41], 0.5, v[68:69] op_sel_hi:[1,0,1]
	v_cvt_pk_bf16_f32 v40, v44, v45
	v_mul_f32_e32 v45, v45, v45
	v_fmac_f32_e32 v45, v44, v44
	v_mul_f32_e32 v44, v47, v47
	v_fmac_f32_e32 v44, v46, v46
	v_cvt_pk_bf16_f32 v41, v46, v47
	v_add_f32_e32 v44, v45, v44
	v_mul_f32_e32 v45, v43, v43
	v_mul_f32_e32 v46, v61, v61
	v_fmac_f32_e32 v45, v42, v42
	v_fmac_f32_e32 v46, v60, v60
	v_add_f32_e32 v45, v45, v46
	v_add_f32_e32 v68, v44, v45
	s_waitcnt vmcnt(12)
	v_lshlrev_b32_e32 v44, 16, v236
	v_and_b32_e32 v45, 0xffff0000, v236
	v_lshlrev_b32_e32 v46, 16, v237
	v_and_b32_e32 v47, 0xffff0000, v237
	v_lshlrev_b32_e32 v62, 16, v238
	v_and_b32_e32 v63, 0xffff0000, v238
	v_pk_fma_f32 v[38:39], v[38:39], 0.5, v[46:47] op_sel_hi:[1,0,1]
	v_pk_fma_f32 v[36:37], v[36:37], 0.5, v[44:45] op_sel_hi:[1,0,1]
	v_lshlrev_b32_e32 v64, 16, v239
	v_and_b32_e32 v65, 0xffff0000, v239
	v_pk_fma_f32 v[46:47], v[32:33], 0.5, v[62:63] op_sel_hi:[1,0,1]
	v_mul_f32_e32 v32, v37, v37
	v_mul_f32_e32 v33, v39, v39
	v_pk_fma_f32 v[44:45], v[34:35], 0.5, v[64:65] op_sel_hi:[1,0,1]
	v_fmac_f32_e32 v32, v36, v36
	v_fmac_f32_e32 v33, v38, v38
	v_add_f32_e32 v32, v32, v33
	v_mul_f32_e32 v33, v47, v47
	v_mul_f32_e32 v34, v45, v45
	v_fmac_f32_e32 v33, v46, v46
	v_fmac_f32_e32 v34, v44, v44
	v_add_f32_e32 v33, v33, v34
	v_add_f32_e32 v32, v32, v33
	v_add_f32_e32 v32, v68, v32
	ds_bpermute_b32 v33, v171, v32
	v_cvt_pk_bf16_f32 v42, v42, v43
	v_cvt_pk_bf16_f32 v43, v60, v61
	v_cvt_pk_bf16_f32 v34, v36, v37
	v_cvt_pk_bf16_f32 v35, v38, v39
	s_waitcnt lgkmcnt(0)
	v_add_f32_e32 v32, v32, v33
	ds_bpermute_b32 v33, v170, v32
	v_cvt_pk_bf16_f32 v36, v46, v47
	v_cvt_pk_bf16_f32 v37, v44, v45
	global_store_dwordx4 v[74:75], v[40:43], off
	global_store_dwordx4 v[74:75], v[34:37], off offset:256
	s_and_saveexec_b64 s[28:29], s[36:37]
	s_cbranch_execz .LBB0_285
	v_lshlrev_b64 v[34:35], 6, v[72:73]
	v_lshl_add_u64 v[34:35], s[10:11], 0, v[34:35]
	v_lshl_add_u64 v[34:35], s[16:17], 2, v[34:35]
	s_lshl_b32 s40, s48, 2
	s_mov_b32 s41, s5
	v_lshl_add_u64 v[34:35], v[34:35], 0, s[40:41]
	s_waitcnt lgkmcnt(0)
	v_add_f32_e32 v32, v32, v33
	global_store_dword v[34:35], v32, off
; __device__ __forceinline__ u32x2 pack4(f32x4 v) { u32x2 w; w.x = cvt_pk_bf16(v[0], v[1]); w.y = cvt_pk_bf16(v[2], v[3]); return w; }
;     __device__ __forceinline__ void gload(Grp& h, size_t off) const {
;         if constexpr (F32IN) { h.f[0] = *(const f32x4*)(hin + off); h.f[1] = *(const f32x4*)(hin + off + 4); h.f[2] = *(const f32x4*)(hin + off + HALF); h.f[3] = *(const f32x4*)(hin + off + HALF + 4); }
;         else { const u32x4 a = *(const u32x4*)(xa + off), b = *(const u32x4*)(xa + off + HALF); h.f[0] = __builtin_bit_cast(f32x4, a); h.f[2] = __builtin_bit_cast(f32x4, b); }
;     }
;     __device__ __forceinline__ void unpack(const Grp& h, int bj, f32x4& v0, f32x4& v1) const {
;         if constexpr (F32IN) { v0 = h.f[2 * bj]; v1 = h.f[2 * bj + 1]; }
;         else { const u32x4 w = __builtin_bit_cast(u32x4, h.f[2 * bj]);
;             v0[0] = __uint_as_float(w.x << 16); v0[1] = __uint_as_float(w.x & 0xffff0000u); v0[2] = __uint_as_float(w.y << 16); v0[3] = __uint_as_float(w.y & 0xffff0000u);
;             v1[0] = __uint_as_float(w.z << 16); v1[1] = __uint_as_float(w.z & 0xffff0000u); v1[2] = __uint_as_float(w.w << 16); v1[3] = __uint_as_float(w.w & 0xffff0000u); }
;     }
;     __device__ __forceinline__ void operator()(const f32x4 (&acc)[2][2][4][2], const Unit& u, int wr, int wc, int fr, int fq) const {
;         Grp h[2];
;         gload(h[0], goff(u, 0, wr, wc, fr, fq));
; #pragma unroll
;         for (int g = 0; g < 8; ++g) {
;             const int ai = g >> 2, m = g & 3; const size_t off = goff(u, g, wr, wc, fr, fq);
;             if (g < 7) gload(h[(g + 1) & 1], goff(u, g + 1, wr, wc, fr, fq));
;             float sq = 0.f;
; #pragma unroll
;             for (int bj = 0; bj < 2; ++bj) { const size_t o = off + bj * HALF; f32x4 h0, h1; unpack(h[g & 1], bj, h0, h1);
;                 h0 = h0 + acc[ai][bj][m][0] * alpha; h1 = h1 + acc[ai][bj][m][1] * alpha;
;                 const u32x2 p0 = pack4(h0), p1 = pack4(h1); u32x4 w; w.x = p0.x; w.y = p0.y; w.z = p1.x; w.w = p1.y; *(u32x4*)(xa + o) = w;
;                 sq += ((h0[0] * h0[0] + h0[1] * h0[1]) + (h0[2] * h0[2] + h0[3] * h0[3])) + ((h1[0] * h1[0] + h1[1] * h1[1]) + (h1[2] * h1[2] + h1[3] * h1[3])); }
;             sq += __shfl_xor(sq, 16); sq += __shfl_xor(sq, 32);
;             if (fq == 0) ssout[(size_t)(u.pm * BM + ai * HALF + wr * 64 + m * 16 + fr) * 16 + u.pn * 4 + wc] = sq;
.LBB0_285:
	s_or_b64 exec, exec, s[28:29]
	v_or_b32_e32 v40, 48, v88
	v_ashrrev_i32_e32 v41, 31, v40
	s_waitcnt lgkmcnt(0)
	v_lshlrev_b64 v[32:33], 11, v[40:41]
	v_lshl_add_u64 v[32:33], s[22:23], 0, v[32:33]
	v_lshl_add_u64 v[32:33], s[18:19], 1, v[32:33]
	v_lshl_add_u64 v[32:33], v[32:33], 0, s[4:5]
	v_lshl_add_u64 v[42:43], v[32:33], 0, v[144:145]
	global_load_dwordx4 v[36:39], v[42:43], off
	global_load_dwordx4 v[32:35], v[42:43], off offset:256
	s_waitcnt vmcnt(14)
	s_waitcnt vmcnt(14)
	v_lshlrev_b32_e32 v44, 16, v240
	v_and_b32_e32 v45, 0xffff0000, v240
	v_lshlrev_b32_e32 v46, 16, v241
	v_and_b32_e32 v47, 0xffff0000, v241
	v_lshlrev_b32_e32 v52, 16, v242
	v_and_b32_e32 v53, 0xffff0000, v242
	v_lshlrev_b32_e32 v54, 16, v243
	v_and_b32_e32 v55, 0xffff0000, v243
	v_pk_fma_f32 v[28:29], v[28:29], 0.5, v[44:45] op_sel_hi:[1,0,1]
	v_pk_fma_f32 v[30:31], v[30:31], 0.5, v[46:47] op_sel_hi:[1,0,1]
	v_pk_fma_f32 v[44:45], v[26:27], 0.5, v[54:55] op_sel_hi:[1,0,1]
	v_pk_fma_f32 v[26:27], v[24:25], 0.5, v[52:53] op_sel_hi:[1,0,1]
	v_cvt_pk_bf16_f32 v24, v28, v29
	v_mul_f32_e32 v29, v29, v29
	v_fmac_f32_e32 v29, v28, v28
	v_mul_f32_e32 v28, v31, v31
	v_fmac_f32_e32 v28, v30, v30
	v_cvt_pk_bf16_f32 v25, v30, v31
	v_add_f32_e32 v28, v29, v28
	v_mul_f32_e32 v29, v27, v27
	v_mul_f32_e32 v30, v45, v45
	v_fmac_f32_e32 v29, v26, v26
	v_fmac_f32_e32 v30, v44, v44
	v_add_f32_e32 v29, v29, v30
	v_add_f32_e32 v52, v28, v29
	s_waitcnt vmcnt(14)
	v_lshlrev_b32_e32 v28, 16, v244
	v_and_b32_e32 v29, 0xffff0000, v244
	v_lshlrev_b32_e32 v30, 16, v245
	v_and_b32_e32 v31, 0xffff0000, v245
	v_lshlrev_b32_e32 v46, 16, v246
	v_and_b32_e32 v47, 0xffff0000, v246
	v_pk_fma_f32 v[22:23], v[22:23], 0.5, v[30:31] op_sel_hi:[1,0,1]
	v_pk_fma_f32 v[20:21], v[20:21], 0.5, v[28:29] op_sel_hi:[1,0,1]
	v_lshlrev_b32_e32 v48, 16, v247
	v_and_b32_e32 v49, 0xffff0000, v247
	v_pk_fma_f32 v[30:31], v[16:17], 0.5, v[46:47] op_sel_hi:[1,0,1]
	v_mul_f32_e32 v16, v21, v21
	v_mul_f32_e32 v17, v23, v23
	v_pk_fma_f32 v[28:29], v[18:19], 0.5, v[48:49] op_sel_hi:[1,0,1]
	v_fmac_f32_e32 v16, v20, v20
	v_fmac_f32_e32 v17, v22, v22
	v_add_f32_e32 v16, v16, v17
	v_mul_f32_e32 v17, v31, v31
	v_mul_f32_e32 v18, v29, v29
	v_fmac_f32_e32 v17, v30, v30
	v_fmac_f32_e32 v18, v28, v28
	v_add_f32_e32 v17, v17, v18
	v_add_f32_e32 v16, v16, v17
	v_add_f32_e32 v16, v52, v16
	ds_bpermute_b32 v17, v171, v16
	v_cvt_pk_bf16_f32 v26, v26, v27
	v_cvt_pk_bf16_f32 v27, v44, v45
	v_cvt_pk_bf16_f32 v18, v20, v21
	v_cvt_pk_bf16_f32 v19, v22, v23
	s_waitcnt lgkmcnt(0)
	v_add_f32_e32 v16, v16, v17
	ds_bpermute_b32 v17, v170, v16
	v_cvt_pk_bf16_f32 v20, v30, v31
	v_cvt_pk_bf16_f32 v21, v28, v29
	global_store_dwordx4 v[58:59], v[24:27], off
	global_store_dwordx4 v[58:59], v[18:21], off offset:256
	s_and_saveexec_b64 s[18:19], s[36:37]
	s_cbranch_execz .LBB0_287
	v_lshlrev_b64 v[18:19], 6, v[56:57]
	v_lshl_add_u64 v[18:19], s[10:11], 0, v[18:19]
	v_lshl_add_u64 v[18:19], s[16:17], 2, v[18:19]
	s_lshl_b32 s4, s48, 2
	v_lshl_add_u64 v[18:19], v[18:19], 0, s[4:5]
	s_waitcnt lgkmcnt(0)
	v_add_f32_e32 v16, v16, v17
	global_store_dword v[18:19], v16, off
.LBB0_287:
	s_or_b64 exec, exec, s[18:19]
	s_waitcnt vmcnt(2)
	v_lshlrev_b32_e32 v16, 16, v36
	s_waitcnt lgkmcnt(0)
	v_and_b32_e32 v17, 0xffff0000, v36
	v_lshlrev_b32_e32 v18, 16, v37
	v_and_b32_e32 v19, 0xffff0000, v37
	v_lshlrev_b32_e32 v20, 16, v38
	v_and_b32_e32 v21, 0xffff0000, v38
	v_lshlrev_b32_e32 v22, 16, v39
	v_and_b32_e32 v23, 0xffff0000, v39
	v_pk_fma_f32 v[12:13], v[12:13], 0.5, v[16:17] op_sel_hi:[1,0,1]
	v_pk_fma_f32 v[14:15], v[14:15], 0.5, v[18:19] op_sel_hi:[1,0,1]
	v_pk_fma_f32 v[16:17], v[10:11], 0.5, v[22:23] op_sel_hi:[1,0,1]
	v_pk_fma_f32 v[10:11], v[8:9], 0.5, v[20:21] op_sel_hi:[1,0,1]
	v_cvt_pk_bf16_f32 v8, v12, v13
	v_mul_f32_e32 v13, v13, v13
	v_fmac_f32_e32 v13, v12, v12
	v_mul_f32_e32 v12, v15, v15
	v_fmac_f32_e32 v12, v14, v14
	v_cvt_pk_bf16_f32 v9, v14, v15
	v_add_f32_e32 v12, v13, v12
	v_mul_f32_e32 v13, v11, v11
	v_mul_f32_e32 v14, v17, v17
	v_fmac_f32_e32 v13, v10, v10
	v_fmac_f32_e32 v14, v16, v16
	v_add_f32_e32 v13, v13, v14
	v_add_f32_e32 v22, v12, v13
	s_waitcnt vmcnt(2)
	v_lshlrev_b32_e32 v12, 16, v32
	v_and_b32_e32 v13, 0xffff0000, v32
	v_lshlrev_b32_e32 v14, 16, v33
	v_and_b32_e32 v15, 0xffff0000, v33
	v_lshlrev_b32_e32 v18, 16, v34
	v_and_b32_e32 v19, 0xffff0000, v34
	v_pk_fma_f32 v[6:7], v[6:7], 0.5, v[14:15] op_sel_hi:[1,0,1]
	v_pk_fma_f32 v[4:5], v[4:5], 0.5, v[12:13] op_sel_hi:[1,0,1]
	v_lshlrev_b32_e32 v20, 16, v35
	v_and_b32_e32 v21, 0xffff0000, v35
	v_pk_fma_f32 v[14:15], v[0:1], 0.5, v[18:19] op_sel_hi:[1,0,1]
	v_mul_f32_e32 v0, v5, v5
	v_mul_f32_e32 v1, v7, v7
	v_pk_fma_f32 v[12:13], v[2:3], 0.5, v[20:21] op_sel_hi:[1,0,1]
	v_fmac_f32_e32 v0, v4, v4
	v_fmac_f32_e32 v1, v6, v6
	v_add_f32_e32 v0, v0, v1
	v_mul_f32_e32 v1, v15, v15
	v_mul_f32_e32 v2, v13, v13
	v_fmac_f32_e32 v1, v14, v14
	v_fmac_f32_e32 v2, v12, v12
	v_add_f32_e32 v1, v1, v2
	v_add_f32_e32 v0, v0, v1
	v_add_f32_e32 v0, v22, v0
	ds_bpermute_b32 v1, v171, v0
	v_cvt_pk_bf16_f32 v10, v10, v11
	v_cvt_pk_bf16_f32 v11, v16, v17
	v_cvt_pk_bf16_f32 v2, v4, v5
	s_waitcnt lgkmcnt(0)
	v_add_f32_e32 v0, v0, v1
	ds_bpermute_b32 v1, v170, v0
	v_cvt_pk_bf16_f32 v3, v6, v7
	v_cvt_pk_bf16_f32 v4, v14, v15
	v_cvt_pk_bf16_f32 v5, v12, v13
	global_store_dwordx4 v[42:43], v[8:11], off
	global_store_dwordx4 v[42:43], v[2:5], off offset:256
	s_and_saveexec_b64 s[18:19], s[36:37]
	s_cbranch_execz .LBB0_289
	v_lshlrev_b64 v[2:3], 6, v[40:41]
	v_lshl_add_u64 v[2:3], s[10:11], 0, v[2:3]
	v_lshl_add_u64 v[2:3], s[16:17], 2, v[2:3]
	s_lshl_b32 s4, s48, 2
	v_lshl_add_u64 v[2:3], v[2:3], 0, s[4:5]
	s_waitcnt lgkmcnt(0)
	v_add_f32_e32 v0, v0, v1
	global_store_dword v[2:3], v0, off

; __device__ __forceinline__ u32x2 pack4(f32x4 v) { u32x2 w; w.x = cvt_pk_bf16(v[0], v[1]); w.y = cvt_pk_bf16(v[2], v[3]); return w; }
;     __device__ __forceinline__ size_t goff(const Unit& u, int g, int wr, int wc, int fr, int fq) const { return (size_t)(u.pm * BM + (g >> 2) * HALF + wr * 64 + (g & 3) * 16 + fr) * 1024 + u.pn * BM + wc * 32 + fq * 8; }
;     __device__ __forceinline__ void gload(Grp& h, size_t off) const {
;         if constexpr (F32IN) { h.f[0] = *(const f32x4*)(hin + off); h.f[1] = *(const f32x4*)(hin + off + 4); h.f[2] = *(const f32x4*)(hin + off + HALF); h.f[3] = *(const f32x4*)(hin + off + HALF + 4); }
;         else { const u32x4 a = *(const u32x4*)(xa + off), b = *(const u32x4*)(xa + off + HALF); h.f[0] = __builtin_bit_cast(f32x4, a); h.f[2] = __builtin_bit_cast(f32x4, b); }
;     }
;     __device__ __forceinline__ void unpack(const Grp& h, int bj, f32x4& v0, f32x4& v1) const {
;         if constexpr (F32IN) { v0 = h.f[2 * bj]; v1 = h.f[2 * bj + 1]; }
;         else { const u32x4 w = __builtin_bit_cast(u32x4, h.f[2 * bj]);
;             v0[0] = __uint_as_float(w.x << 16); v0[1] = __uint_as_float(w.x & 0xffff0000u); v0[2] = __uint_as_float(w.y << 16); v0[3] = __uint_as_float(w.y & 0xffff0000u);
;             v1[0] = __uint_as_float(w.z << 16); v1[1] = __uint_as_float(w.z & 0xffff0000u); v1[2] = __uint_as_float(w.w << 16); v1[3] = __uint_as_float(w.w & 0xffff0000u); }
;     }
;     __device__ __forceinline__ void operator()(const f32x4 (&acc)[2][2][4][2], const Unit& u, int wr, int wc, int fr, int fq) const {
;         Grp h[2];
;         gload(h[0], goff(u, 0, wr, wc, fr, fq));
; #pragma unroll
;         for (int g = 0; g < 8; ++g) {
;             const int ai = g >> 2, m = g & 3; const size_t off = goff(u, g, wr, wc, fr, fq);
;             if (g < 7) gload(h[(g + 1) & 1], goff(u, g + 1, wr, wc, fr, fq));
;             float sq = 0.f;
; #pragma unroll
;             for (int bj = 0; bj < 2; ++bj) { const size_t o = off + bj * HALF; f32x4 h0, h1; unpack(h[g & 1], bj, h0, h1);
;                 h0 = h0 + acc[ai][bj][m][0] * alpha; h1 = h1 + acc[ai][bj][m][1] * alpha;
;                 const u32x2 p0 = pack4(h0), p1 = pack4(h1); u32x4 w; w.x = p0.x; w.y = p0.y; w.z = p1.x; w.w = p1.y; *(u32x4*)(xa + o) = w;
.LBB0_625:
	v_lshl_add_u32 v162, s28, 8, v157
	v_ashrrev_i32_e32 v163, 31, v162
	s_lshl_b32 s28, s18, 8
	s_ashr_i32 s29, s28, 31
	v_lshlrev_b64 v[128:129], 11, v[162:163]
	v_lshl_add_u64 v[128:129], s[22:23], 0, v[128:129]
	s_lshl_b64 s[40:41], s[28:29], 1
	v_lshl_add_u64 v[128:129], v[128:129], 0, s[40:41]
	s_lshl_b32 s4, s55, 1
	v_lshl_add_u64 v[128:129], v[128:129], 0, s[4:5]
	v_lshlrev_b32_e32 v144, 1, v156
	v_lshl_add_u64 v[180:181], v[128:129], 0, v[144:145]
	global_load_dwordx4 v[172:175], v[180:181], off
	global_load_dwordx4 v[176:179], v[180:181], off offset:256
	v_or_b32_e32 v164, 16, v162
	v_ashrrev_i32_e32 v165, 31, v164
	v_lshlrev_b64 v[128:129], 11, v[164:165]
	v_lshl_add_u64 v[128:129], s[22:23], 0, v[128:129]
	v_lshl_add_u64 v[128:129], v[128:129], 0, s[40:41]
	v_lshl_add_u64 v[128:129], v[128:129], 0, s[4:5]
	v_lshl_add_u64 v[166:167], v[128:129], 0, v[144:145]
	global_load_dwordx4 v[132:135], v[166:167], off
	global_load_dwordx4 v[128:131], v[166:167], off offset:256
	v_add_co_u32_e32 v182, vcc, 0x10000, v180
	s_nop 1
	v_addc_co_u32_e32 v183, vcc, 0, v181, vcc
	global_load_dwordx4 v[190:193], v[182:183], off
	global_load_dwordx4 v[194:197], v[182:183], off offset:256
	v_add_co_u32_e32 v182, vcc, 0x18000, v180
	s_nop 1
	v_addc_co_u32_e32 v183, vcc, 0, v181, vcc
	global_load_dwordx4 v[216:219], v[182:183], off
	global_load_dwordx4 v[220:223], v[182:183], off offset:256
	v_add_co_u32_e32 v182, vcc, 0x40000, v180
	s_nop 1
	v_addc_co_u32_e32 v183, vcc, 0, v181, vcc
	global_load_dwordx4 v[224:227], v[182:183], off
	global_load_dwordx4 v[228:231], v[182:183], off offset:256
	v_add_co_u32_e32 v182, vcc, 0x48000, v180
	s_nop 1
	v_addc_co_u32_e32 v183, vcc, 0, v181, vcc
	global_load_dwordx4 v[232:235], v[182:183], off
	global_load_dwordx4 v[236:239], v[182:183], off offset:256
	v_add_co_u32_e32 v182, vcc, 0x50000, v180
	s_nop 1
	v_addc_co_u32_e32 v183, vcc, 0, v181, vcc
	global_load_dwordx4 v[240:243], v[182:183], off
	global_load_dwordx4 v[244:247], v[182:183], off offset:256
	v_and_b32_e32 v171, 64, v203
	v_xor_b32_e32 v170, 16, v203
	v_add_u32_e32 v171, 64, v171
	v_xor_b32_e32 v182, 32, v203
	v_cmp_lt_i32_e32 vcc, v170, v171
	s_lshl_b32 s18, s18, 2
	s_ashr_i32 s19, s18, 31
	v_cndmask_b32_e32 v170, v203, v170, vcc
	v_cmp_lt_i32_e32 vcc, v182, v171
	v_lshlrev_b32_e32 v171, 2, v170
	s_waitcnt vmcnt(12)
	v_and_b32_e32 v183, 0xffff0000, v172
	v_cndmask_b32_e32 v182, v203, v182, vcc
	v_lshlrev_b32_e32 v170, 2, v182
	v_lshlrev_b32_e32 v182, 16, v172
	v_lshlrev_b32_e32 v172, 16, v173
	v_and_b32_e32 v173, 0xffff0000, v173
	v_lshlrev_b32_e32 v184, 16, v174
	v_and_b32_e32 v185, 0xffff0000, v174
	v_lshlrev_b32_e32 v174, 16, v175
	v_and_b32_e32 v175, 0xffff0000, v175
	v_lshlrev_b32_e32 v186, 16, v176
	v_and_b32_e32 v187, 0xffff0000, v176
	v_lshlrev_b32_e32 v176, 16, v177
	v_and_b32_e32 v177, 0xffff0000, v177
	v_lshlrev_b32_e32 v188, 16, v178
	v_and_b32_e32 v189, 0xffff0000, v178
	v_lshlrev_b32_e32 v178, 16, v179
	v_and_b32_e32 v179, 0xffff0000, v179
	v_pk_add_f32 v[126:127], v[126:127], v[172:173]
	v_pk_add_f32 v[124:125], v[124:125], v[182:183]
	v_pk_add_f32 v[122:123], v[122:123], v[174:175]
	v_pk_add_f32 v[120:121], v[120:121], v[184:185]
	v_pk_add_f32 v[118:119], v[118:119], v[176:177]
	v_pk_add_f32 v[116:117], v[116:117], v[186:187]
	v_pk_add_f32 v[172:173], v[114:115], v[178:179]
	v_pk_add_f32 v[174:175], v[112:113], v[188:189]
	v_cvt_pk_bf16_f32 v112, v124, v125
	v_cvt_pk_bf16_f32 v113, v126, v127
	v_mul_f32_e32 v114, v125, v125
	v_mul_f32_e32 v115, v127, v127
	v_mul_f32_e32 v125, v121, v121
	v_mul_f32_e32 v127, v123, v123
	v_mul_f32_e32 v176, v117, v117
	v_mul_f32_e32 v177, v119, v119
	v_mul_f32_e32 v178, v175, v175
	v_mul_f32_e32 v179, v173, v173
	v_fmac_f32_e32 v114, v124, v124
	v_fmac_f32_e32 v115, v126, v126
	v_fmac_f32_e32 v125, v120, v120
	v_fmac_f32_e32 v127, v122, v122
	v_fmac_f32_e32 v176, v116, v116
	v_fmac_f32_e32 v177, v118, v118
	v_fmac_f32_e32 v178, v174, v174
	v_fmac_f32_e32 v179, v172, v172
	v_add_f32_e32 v114, v114, v115
	v_add_f32_e32 v115, v125, v127
	v_add_f32_e32 v124, v176, v177
	v_add_f32_e32 v125, v178, v179
	v_add_f32_e32 v114, v114, v115
	v_add_f32_e32 v115, v124, v125
	v_add_f32_e32 v124, v114, v115
	ds_bpermute_b32 v125, v171, v124
	v_cvt_pk_bf16_f32 v114, v120, v121
	v_cvt_pk_bf16_f32 v115, v122, v123
	global_store_dwordx4 v[180:181], v[112:115], off
	s_waitcnt lgkmcnt(0)
	s_nop 0
	v_add_f32_e32 v112, v124, v125
	ds_bpermute_b32 v113, v170, v112
	v_cvt_pk_bf16_f32 v114, v116, v117
	v_cvt_pk_bf16_f32 v115, v118, v119
	v_cvt_pk_bf16_f32 v116, v174, v175
	v_cvt_pk_bf16_f32 v117, v172, v173
	global_store_dwordx4 v[180:181], v[114:117], off offset:256
	s_and_saveexec_b64 s[40:41], s[36:37]
	s_cbranch_execz .LBB0_627
	v_lshlrev_b64 v[114:115], 6, v[162:163]
	v_lshl_add_u64 v[114:115], s[6:7], 0, v[114:115]
	v_lshl_add_u64 v[114:115], s[18:19], 2, v[114:115]
	s_lshl_b32 s42, s54, 2
	s_mov_b32 s43, s5
	v_lshl_add_u64 v[114:115], v[114:115], 0, s[42:43]
	s_waitcnt lgkmcnt(0)
	v_add_f32_e32 v112, v112, v113
	global_store_dword v[114:115], v112, off
; __device__ __forceinline__ u32x2 pack4(f32x4 v) { u32x2 w; w.x = cvt_pk_bf16(v[0], v[1]); w.y = cvt_pk_bf16(v[2], v[3]); return w; }
;     __device__ __forceinline__ void gload(Grp& h, size_t off) const {
;         if constexpr (F32IN) { h.f[0] = *(const f32x4*)(hin + off); h.f[1] = *(const f32x4*)(hin + off + 4); h.f[2] = *(const f32x4*)(hin + off + HALF); h.f[3] = *(const f32x4*)(hin + off + HALF + 4); }
;         else { const u32x4 a = *(const u32x4*)(xa + off), b = *(const u32x4*)(xa + off + HALF); h.f[0] = __builtin_bit_cast(f32x4, a); h.f[2] = __builtin_bit_cast(f32x4, b); }
;     }
;     __device__ __forceinline__ void unpack(const Grp& h, int bj, f32x4& v0, f32x4& v1) const {
;         if constexpr (F32IN) { v0 = h.f[2 * bj]; v1 = h.f[2 * bj + 1]; }
;         else { const u32x4 w = __builtin_bit_cast(u32x4, h.f[2 * bj]);
;             v0[0] = __uint_as_float(w.x << 16); v0[1] = __uint_as_float(w.x & 0xffff0000u); v0[2] = __uint_as_float(w.y << 16); v0[3] = __uint_as_float(w.y & 0xffff0000u);
;             v1[0] = __uint_as_float(w.z << 16); v1[1] = __uint_as_float(w.z & 0xffff0000u); v1[2] = __uint_as_float(w.w << 16); v1[3] = __uint_as_float(w.w & 0xffff0000u); }
;     }
;     __device__ __forceinline__ void operator()(const f32x4 (&acc)[2][2][4][2], const Unit& u, int wr, int wc, int fr, int fq) const {
;         Grp h[2];
;         gload(h[0], goff(u, 0, wr, wc, fr, fq));
; #pragma unroll
;         for (int g = 0; g < 8; ++g) {
;             const int ai = g >> 2, m = g & 3; const size_t off = goff(u, g, wr, wc, fr, fq);
;             if (g < 7) gload(h[(g + 1) & 1], goff(u, g + 1, wr, wc, fr, fq));
;             float sq = 0.f;
; #pragma unroll
;             for (int bj = 0; bj < 2; ++bj) { const size_t o = off + bj * HALF; f32x4 h0, h1; unpack(h[g & 1], bj, h0, h1);
;                 h0 = h0 + acc[ai][bj][m][0] * alpha; h1 = h1 + acc[ai][bj][m][1] * alpha;
;                 const u32x2 p0 = pack4(h0), p1 = pack4(h1); u32x4 w; w.x = p0.x; w.y = p0.y; w.z = p1.x; w.w = p1.y; *(u32x4*)(xa + o) = w;
;                 sq += ((h0[0] * h0[0] + h0[1] * h0[1]) + (h0[2] * h0[2] + h0[3] * h0[3])) + ((h1[0] * h1[0] + h1[1] * h1[1]) + (h1[2] * h1[2] + h1[3] * h1[3])); }
;             sq += __shfl_xor(sq, 16); sq += __shfl_xor(sq, 32);
;             if (fq == 0) ssout[(size_t)(u.pm * BM + ai * HALF + wr * 64 + m * 16 + fr) * 16 + u.pn * 4 + wc] = sq;
.LBB0_627:
	s_or_b64 exec, exec, s[40:41]
	v_or_b32_e32 v120, 32, v162
	v_ashrrev_i32_e32 v121, 31, v120
	s_waitcnt lgkmcnt(0)
	v_lshlrev_b64 v[112:113], 11, v[120:121]
	v_lshl_add_u64 v[112:113], s[22:23], 0, v[112:113]
	v_lshl_add_u64 v[112:113], s[28:29], 1, v[112:113]
	v_lshl_add_u64 v[112:113], v[112:113], 0, s[4:5]
	v_lshl_add_u64 v[122:123], v[112:113], 0, v[144:145]
	s_waitcnt vmcnt(12)
	v_lshlrev_b32_e32 v124, 16, v132
	v_and_b32_e32 v125, 0xffff0000, v132
	v_lshlrev_b32_e32 v126, 16, v133
	v_and_b32_e32 v127, 0xffff0000, v133
	v_lshlrev_b32_e32 v132, 16, v134
	v_and_b32_e32 v133, 0xffff0000, v134
	v_lshlrev_b32_e32 v134, 16, v135
	v_and_b32_e32 v135, 0xffff0000, v135
	v_pk_add_f32 v[108:109], v[108:109], v[124:125]
	v_pk_add_f32 v[110:111], v[110:111], v[126:127]
	v_pk_add_f32 v[124:125], v[106:107], v[134:135]
	v_pk_add_f32 v[106:107], v[104:105], v[132:133]
	v_cvt_pk_bf16_f32 v104, v108, v109
	v_mul_f32_e32 v109, v109, v109
	v_fmac_f32_e32 v109, v108, v108
	v_mul_f32_e32 v108, v111, v111
	v_fmac_f32_e32 v108, v110, v110
	v_cvt_pk_bf16_f32 v105, v110, v111
	v_add_f32_e32 v108, v109, v108
	v_mul_f32_e32 v109, v107, v107
	v_mul_f32_e32 v110, v125, v125
	v_fmac_f32_e32 v109, v106, v106
	v_fmac_f32_e32 v110, v124, v124
	v_add_f32_e32 v109, v109, v110
	v_add_f32_e32 v132, v108, v109
	v_lshlrev_b32_e32 v108, 16, v128
	v_and_b32_e32 v109, 0xffff0000, v128
	v_lshlrev_b32_e32 v110, 16, v129
	v_and_b32_e32 v111, 0xffff0000, v129
	v_lshlrev_b32_e32 v126, 16, v130
	v_and_b32_e32 v127, 0xffff0000, v130
	v_pk_add_f32 v[102:103], v[102:103], v[110:111]
	v_pk_add_f32 v[100:101], v[100:101], v[108:109]
	v_lshlrev_b32_e32 v128, 16, v131
	v_and_b32_e32 v129, 0xffff0000, v131
	v_pk_add_f32 v[110:111], v[96:97], v[126:127]
	v_mul_f32_e32 v96, v101, v101
	v_mul_f32_e32 v97, v103, v103
	v_pk_add_f32 v[108:109], v[98:99], v[128:129]
	v_fmac_f32_e32 v96, v100, v100
	v_fmac_f32_e32 v97, v102, v102
	v_add_f32_e32 v96, v96, v97
	v_mul_f32_e32 v97, v111, v111
	v_mul_f32_e32 v98, v109, v109
	v_fmac_f32_e32 v97, v110, v110
	v_fmac_f32_e32 v98, v108, v108
	v_add_f32_e32 v97, v97, v98
	v_add_f32_e32 v96, v96, v97
	v_add_f32_e32 v96, v132, v96
	ds_bpermute_b32 v97, v171, v96
	v_cvt_pk_bf16_f32 v106, v106, v107
	v_cvt_pk_bf16_f32 v107, v124, v125
	v_cvt_pk_bf16_f32 v98, v100, v101
	v_cvt_pk_bf16_f32 v99, v102, v103
	s_waitcnt lgkmcnt(0)
	v_add_f32_e32 v96, v96, v97
	ds_bpermute_b32 v97, v170, v96
	v_cvt_pk_bf16_f32 v100, v110, v111
	v_cvt_pk_bf16_f32 v101, v108, v109
	global_store_dwordx4 v[166:167], v[104:107], off
	global_store_dwordx4 v[166:167], v[98:101], off offset:256
	s_and_saveexec_b64 s[40:41], s[36:37]
	s_cbranch_execz .LBB0_629
	v_lshlrev_b64 v[98:99], 6, v[164:165]
	v_lshl_add_u64 v[98:99], s[6:7], 0, v[98:99]
	v_lshl_add_u64 v[98:99], s[18:19], 2, v[98:99]
	s_lshl_b32 s42, s54, 2
	s_mov_b32 s43, s5
	v_lshl_add_u64 v[98:99], v[98:99], 0, s[42:43]
	s_waitcnt lgkmcnt(0)
	v_add_f32_e32 v96, v96, v97
	global_store_dword v[98:99], v96, off
.LBB0_629:
	s_or_b64 exec, exec, s[40:41]
	v_or_b32_e32 v104, 48, v162
	v_ashrrev_i32_e32 v105, 31, v104
	s_waitcnt lgkmcnt(0)
	v_lshlrev_b64 v[96:97], 11, v[104:105]
	v_lshl_add_u64 v[96:97], s[22:23], 0, v[96:97]
	v_lshl_add_u64 v[96:97], s[28:29], 1, v[96:97]
	v_lshl_add_u64 v[96:97], v[96:97], 0, s[4:5]
	v_lshl_add_u64 v[106:107], v[96:97], 0, v[144:145]
	s_waitcnt vmcnt(12)
	s_waitcnt vmcnt(12)
	v_lshlrev_b32_e32 v108, 16, v190
	v_and_b32_e32 v109, 0xffff0000, v190
	v_lshlrev_b32_e32 v110, 16, v191
	v_and_b32_e32 v111, 0xffff0000, v191
	v_lshlrev_b32_e32 v116, 16, v192
	v_and_b32_e32 v117, 0xffff0000, v192
	v_lshlrev_b32_e32 v118, 16, v193
	v_and_b32_e32 v119, 0xffff0000, v193
	v_pk_add_f32 v[92:93], v[92:93], v[108:109]
	v_pk_add_f32 v[94:95], v[94:95], v[110:111]
	v_pk_add_f32 v[108:109], v[90:91], v[118:119]
	v_pk_add_f32 v[90:91], v[88:89], v[116:117]
	v_cvt_pk_bf16_f32 v88, v92, v93
	v_mul_f32_e32 v93, v93, v93
	v_fmac_f32_e32 v93, v92, v92
	v_mul_f32_e32 v92, v95, v95
	v_fmac_f32_e32 v92, v94, v94
	v_cvt_pk_bf16_f32 v89, v94, v95
	v_add_f32_e32 v92, v93, v92
	v_mul_f32_e32 v93, v91, v91
	v_mul_f32_e32 v94, v109, v109
	v_fmac_f32_e32 v93, v90, v90
	v_fmac_f32_e32 v94, v108, v108
	v_add_f32_e32 v93, v93, v94
	v_add_f32_e32 v116, v92, v93
	s_waitcnt vmcnt(12)
	v_lshlrev_b32_e32 v92, 16, v194
	v_and_b32_e32 v93, 0xffff0000, v194
	v_lshlrev_b32_e32 v94, 16, v195
	v_and_b32_e32 v95, 0xffff0000, v195
	v_lshlrev_b32_e32 v110, 16, v196
	v_and_b32_e32 v111, 0xffff0000, v196
	v_pk_add_f32 v[86:87], v[86:87], v[94:95]
	v_pk_add_f32 v[84:85], v[84:85], v[92:93]
	v_lshlrev_b32_e32 v112, 16, v197
	v_and_b32_e32 v113, 0xffff0000, v197
	v_pk_add_f32 v[94:95], v[80:81], v[110:111]
	v_mul_f32_e32 v80, v85, v85
	v_mul_f32_e32 v81, v87, v87
	v_pk_add_f32 v[92:93], v[82:83], v[112:113]
	v_fmac_f32_e32 v80, v84, v84
	v_fmac_f32_e32 v81, v86, v86
	v_add_f32_e32 v80, v80, v81
	v_mul_f32_e32 v81, v95, v95
	v_mul_f32_e32 v82, v93, v93
	v_fmac_f32_e32 v81, v94, v94
	v_fmac_f32_e32 v82, v92, v92
	v_add_f32_e32 v81, v81, v82
	v_add_f32_e32 v80, v80, v81
	v_add_f32_e32 v80, v116, v80
	ds_bpermute_b32 v81, v171, v80
	v_cvt_pk_bf16_f32 v90, v90, v91
	v_cvt_pk_bf16_f32 v91, v108, v109
	v_cvt_pk_bf16_f32 v82, v84, v85
	v_cvt_pk_bf16_f32 v83, v86, v87
	s_waitcnt lgkmcnt(0)
	v_add_f32_e32 v80, v80, v81
	ds_bpermute_b32 v81, v170, v80
	v_cvt_pk_bf16_f32 v84, v94, v95
	v_cvt_pk_bf16_f32 v85, v92, v93
	global_store_dwordx4 v[122:123], v[88:91], off
	global_store_dwordx4 v[122:123], v[82:85], off offset:256
	s_and_saveexec_b64 s[40:41], s[36:37]
	s_cbranch_execz .LBB0_631
	v_lshlrev_b64 v[82:83], 6, v[120:121]
	v_lshl_add_u64 v[82:83], s[6:7], 0, v[82:83]
	v_lshl_add_u64 v[82:83], s[18:19], 2, v[82:83]
	s_lshl_b32 s42, s54, 2
	s_mov_b32 s43, s5
	v_lshl_add_u64 v[82:83], v[82:83], 0, s[42:43]
	s_waitcnt lgkmcnt(0)
	v_add_f32_e32 v80, v80, v81
	global_store_dword v[82:83], v80, off
; __device__ __forceinline__ u32x2 pack4(f32x4 v) { u32x2 w; w.x = cvt_pk_bf16(v[0], v[1]); w.y = cvt_pk_bf16(v[2], v[3]); return w; }
;     __device__ __forceinline__ void gload(Grp& h, size_t off) const {
;         if constexpr (F32IN) { h.f[0] = *(const f32x4*)(hin + off); h.f[1] = *(const f32x4*)(hin + off + 4); h.f[2] = *(const f32x4*)(hin + off + HALF); h.f[3] = *(const f32x4*)(hin + off + HALF + 4); }
;         else { const u32x4 a = *(const u32x4*)(xa + off), b = *(const u32x4*)(xa + off + HALF); h.f[0] = __builtin_bit_cast(f32x4, a); h.f[2] = __builtin_bit_cast(f32x4, b); }
;     }
;     __device__ __forceinline__ void unpack(const Grp& h, int bj, f32x4& v0, f32x4& v1) const {
;         if constexpr (F32IN) { v0 = h.f[2 * bj]; v1 = h.f[2 * bj + 1]; }
;         else { const u32x4 w = __builtin_bit_cast(u32x4, h.f[2 * bj]);
;             v0[0] = __uint_as_float(w.x << 16); v0[1] = __uint_as_float(w.x & 0xffff0000u); v0[2] = __uint_as_float(w.y << 16); v0[3] = __uint_as_float(w.y & 0xffff0000u);
;             v1[0] = __uint_as_float(w.z << 16); v1[1] = __uint_as_float(w.z & 0xffff0000u); v1[2] = __uint_as_float(w.w << 16); v1[3] = __uint_as_float(w.w & 0xffff0000u); }
;     }
;     __device__ __forceinline__ void operator()(const f32x4 (&acc)[2][2][4][2], const Unit& u, int wr, int wc, int fr, int fq) const {
;         Grp h[2];
;         gload(h[0], goff(u, 0, wr, wc, fr, fq));
; #pragma unroll
;         for (int g = 0; g < 8; ++g) {
;             const int ai = g >> 2, m = g & 3; const size_t off = goff(u, g, wr, wc, fr, fq);
;             if (g < 7) gload(h[(g + 1) & 1], goff(u, g + 1, wr, wc, fr, fq));
;             float sq = 0.f;
; #pragma unroll
;             for (int bj = 0; bj < 2; ++bj) { const size_t o = off + bj * HALF; f32x4 h0, h1; unpack(h[g & 1], bj, h0, h1);
;                 h0 = h0 + acc[ai][bj][m][0] * alpha; h1 = h1 + acc[ai][bj][m][1] * alpha;
;                 const u32x2 p0 = pack4(h0), p1 = pack4(h1); u32x4 w; w.x = p0.x; w.y = p0.y; w.z = p1.x; w.w = p1.y; *(u32x4*)(xa + o) = w;
;                 sq += ((h0[0] * h0[0] + h0[1] * h0[1]) + (h0[2] * h0[2] + h0[3] * h0[3])) + ((h1[0] * h1[0] + h1[1] * h1[1]) + (h1[2] * h1[2] + h1[3] * h1[3])); }
;             sq += __shfl_xor(sq, 16); sq += __shfl_xor(sq, 32);
;             if (fq == 0) ssout[(size_t)(u.pm * BM + ai * HALF + wr * 64 + m * 16 + fr) * 16 + u.pn * 4 + wc] = sq;
.LBB0_631:
	s_or_b64 exec, exec, s[40:41]
	v_add_u32_e32 v88, 0x80, v162
	v_ashrrev_i32_e32 v89, 31, v88
	s_waitcnt lgkmcnt(0)
	v_lshlrev_b64 v[80:81], 11, v[88:89]
	v_lshl_add_u64 v[80:81], s[22:23], 0, v[80:81]
	v_lshl_add_u64 v[80:81], s[28:29], 1, v[80:81]
	v_lshl_add_u64 v[80:81], v[80:81], 0, s[4:5]
	v_lshl_add_u64 v[90:91], v[80:81], 0, v[144:145]
	s_waitcnt vmcnt(12)
	s_waitcnt vmcnt(12)
	v_lshlrev_b32_e32 v92, 16, v216
	v_and_b32_e32 v93, 0xffff0000, v216
	v_lshlrev_b32_e32 v94, 16, v217
	v_and_b32_e32 v95, 0xffff0000, v217
	v_lshlrev_b32_e32 v100, 16, v218
	v_and_b32_e32 v101, 0xffff0000, v218
	v_lshlrev_b32_e32 v102, 16, v219
	v_and_b32_e32 v103, 0xffff0000, v219
	v_pk_add_f32 v[76:77], v[76:77], v[92:93]
	v_pk_add_f32 v[78:79], v[78:79], v[94:95]
	v_pk_add_f32 v[92:93], v[74:75], v[102:103]
	v_pk_add_f32 v[74:75], v[72:73], v[100:101]
	v_cvt_pk_bf16_f32 v72, v76, v77
	v_mul_f32_e32 v77, v77, v77
	v_fmac_f32_e32 v77, v76, v76
	v_mul_f32_e32 v76, v79, v79
	v_fmac_f32_e32 v76, v78, v78
	v_cvt_pk_bf16_f32 v73, v78, v79
	v_add_f32_e32 v76, v77, v76
	v_mul_f32_e32 v77, v75, v75
	v_mul_f32_e32 v78, v93, v93
	v_fmac_f32_e32 v77, v74, v74
	v_fmac_f32_e32 v78, v92, v92
	v_add_f32_e32 v77, v77, v78
	v_add_f32_e32 v100, v76, v77
	s_waitcnt vmcnt(12)
	v_lshlrev_b32_e32 v76, 16, v220
	v_and_b32_e32 v77, 0xffff0000, v220
	v_lshlrev_b32_e32 v78, 16, v221
	v_and_b32_e32 v79, 0xffff0000, v221
	v_lshlrev_b32_e32 v94, 16, v222
	v_and_b32_e32 v95, 0xffff0000, v222
	v_pk_add_f32 v[70:71], v[70:71], v[78:79]
	v_pk_add_f32 v[68:69], v[68:69], v[76:77]
	v_lshlrev_b32_e32 v96, 16, v223
	v_and_b32_e32 v97, 0xffff0000, v223
	v_pk_add_f32 v[78:79], v[64:65], v[94:95]
	v_mul_f32_e32 v64, v69, v69
	v_mul_f32_e32 v65, v71, v71
	v_pk_add_f32 v[76:77], v[66:67], v[96:97]
	v_fmac_f32_e32 v64, v68, v68
	v_fmac_f32_e32 v65, v70, v70
	v_add_f32_e32 v64, v64, v65
	v_mul_f32_e32 v65, v79, v79
	v_mul_f32_e32 v66, v77, v77
	v_fmac_f32_e32 v65, v78, v78
	v_fmac_f32_e32 v66, v76, v76
	v_add_f32_e32 v65, v65, v66
	v_add_f32_e32 v64, v64, v65
	v_add_f32_e32 v64, v100, v64
	ds_bpermute_b32 v65, v171, v64
	v_cvt_pk_bf16_f32 v74, v74, v75
	v_cvt_pk_bf16_f32 v75, v92, v93
	v_cvt_pk_bf16_f32 v66, v68, v69
	v_cvt_pk_bf16_f32 v67, v70, v71
	s_waitcnt lgkmcnt(0)
	v_add_f32_e32 v64, v64, v65
	ds_bpermute_b32 v65, v170, v64
	v_cvt_pk_bf16_f32 v68, v78, v79
	v_cvt_pk_bf16_f32 v69, v76, v77
	global_store_dwordx4 v[106:107], v[72:75], off
	global_store_dwordx4 v[106:107], v[66:69], off offset:256
	s_and_saveexec_b64 s[40:41], s[36:37]
	s_cbranch_execz .LBB0_633
	v_lshlrev_b64 v[66:67], 6, v[104:105]
	v_lshl_add_u64 v[66:67], s[6:7], 0, v[66:67]
	v_lshl_add_u64 v[66:67], s[18:19], 2, v[66:67]
	s_lshl_b32 s42, s54, 2
	s_mov_b32 s43, s5
	v_lshl_add_u64 v[66:67], v[66:67], 0, s[42:43]
	s_waitcnt lgkmcnt(0)
	v_add_f32_e32 v64, v64, v65
	global_store_dword v[66:67], v64, off
.LBB0_633:
	s_or_b64 exec, exec, s[40:41]
	v_or_b32_e32 v72, 16, v88
	v_ashrrev_i32_e32 v73, 31, v72
	s_waitcnt lgkmcnt(0)
	v_lshlrev_b64 v[64:65], 11, v[72:73]
	v_lshl_add_u64 v[64:65], s[22:23], 0, v[64:65]
	v_lshl_add_u64 v[64:65], s[28:29], 1, v[64:65]
	v_lshl_add_u64 v[64:65], v[64:65], 0, s[4:5]
	v_lshl_add_u64 v[74:75], v[64:65], 0, v[144:145]
	s_waitcnt vmcnt(12)
	s_waitcnt vmcnt(12)
	v_lshlrev_b32_e32 v76, 16, v224
	v_and_b32_e32 v77, 0xffff0000, v224
	v_lshlrev_b32_e32 v78, 16, v225
	v_and_b32_e32 v79, 0xffff0000, v225
	v_lshlrev_b32_e32 v84, 16, v226
	v_and_b32_e32 v85, 0xffff0000, v226
	v_lshlrev_b32_e32 v86, 16, v227
	v_and_b32_e32 v87, 0xffff0000, v227
	v_pk_add_f32 v[60:61], v[60:61], v[76:77]
	v_pk_add_f32 v[62:63], v[62:63], v[78:79]
	v_pk_add_f32 v[76:77], v[58:59], v[86:87]
	v_pk_add_f32 v[58:59], v[56:57], v[84:85]
	v_cvt_pk_bf16_f32 v56, v60, v61
	v_mul_f32_e32 v61, v61, v61
	v_fmac_f32_e32 v61, v60, v60
	v_mul_f32_e32 v60, v63, v63
	v_fmac_f32_e32 v60, v62, v62
	v_cvt_pk_bf16_f32 v57, v62, v63
	v_add_f32_e32 v60, v61, v60
	v_mul_f32_e32 v61, v59, v59
	v_mul_f32_e32 v62, v77, v77
	v_fmac_f32_e32 v61, v58, v58
	v_fmac_f32_e32 v62, v76, v76
	v_add_f32_e32 v61, v61, v62
	v_add_f32_e32 v84, v60, v61
	s_waitcnt vmcnt(12)
	v_lshlrev_b32_e32 v60, 16, v228
	v_and_b32_e32 v61, 0xffff0000, v228
	v_lshlrev_b32_e32 v62, 16, v229
	v_and_b32_e32 v63, 0xffff0000, v229
	v_lshlrev_b32_e32 v78, 16, v230
	v_and_b32_e32 v79, 0xffff0000, v230
	v_pk_add_f32 v[54:55], v[54:55], v[62:63]
	v_pk_add_f32 v[52:53], v[52:53], v[60:61]
	v_lshlrev_b32_e32 v80, 16, v231
	v_and_b32_e32 v81, 0xffff0000, v231
	v_pk_add_f32 v[62:63], v[48:49], v[78:79]
	v_mul_f32_e32 v48, v53, v53
	v_mul_f32_e32 v49, v55, v55
	v_pk_add_f32 v[60:61], v[50:51], v[80:81]
	v_fmac_f32_e32 v48, v52, v52
	v_fmac_f32_e32 v49, v54, v54
	v_add_f32_e32 v48, v48, v49
	v_mul_f32_e32 v49, v63, v63
	v_mul_f32_e32 v50, v61, v61
	v_fmac_f32_e32 v49, v62, v62
	v_fmac_f32_e32 v50, v60, v60
	v_add_f32_e32 v49, v49, v50
	v_add_f32_e32 v48, v48, v49
	v_add_f32_e32 v48, v84, v48
	ds_bpermute_b32 v49, v171, v48
	v_cvt_pk_bf16_f32 v58, v58, v59
	v_cvt_pk_bf16_f32 v59, v76, v77
	v_cvt_pk_bf16_f32 v50, v52, v53
	v_cvt_pk_bf16_f32 v51, v54, v55
	s_waitcnt lgkmcnt(0)
	v_add_f32_e32 v48, v48, v49
	ds_bpermute_b32 v49, v170, v48
	v_cvt_pk_bf16_f32 v52, v62, v63
	v_cvt_pk_bf16_f32 v53, v60, v61
	global_store_dwordx4 v[90:91], v[56:59], off
	global_store_dwordx4 v[90:91], v[50:53], off offset:256
	s_and_saveexec_b64 s[40:41], s[36:37]
	s_cbranch_execz .LBB0_635
	v_lshlrev_b64 v[50:51], 6, v[88:89]
	v_lshl_add_u64 v[50:51], s[6:7], 0, v[50:51]
	v_lshl_add_u64 v[50:51], s[18:19], 2, v[50:51]
	s_lshl_b32 s42, s54, 2
	s_mov_b32 s43, s5
	v_lshl_add_u64 v[50:51], v[50:51], 0, s[42:43]
	s_waitcnt lgkmcnt(0)
	v_add_f32_e32 v48, v48, v49
	global_store_dword v[50:51], v48, off
; __device__ __forceinline__ u32x2 pack4(f32x4 v) { u32x2 w; w.x = cvt_pk_bf16(v[0], v[1]); w.y = cvt_pk_bf16(v[2], v[3]); return w; }
;     __device__ __forceinline__ void gload(Grp& h, size_t off) const {
;         if constexpr (F32IN) { h.f[0] = *(const f32x4*)(hin + off); h.f[1] = *(const f32x4*)(hin + off + 4); h.f[2] = *(const f32x4*)(hin + off + HALF); h.f[3] = *(const f32x4*)(hin + off + HALF + 4); }
;         else { const u32x4 a = *(const u32x4*)(xa + off), b = *(const u32x4*)(xa + off + HALF); h.f[0] = __builtin_bit_cast(f32x4, a); h.f[2] = __builtin_bit_cast(f32x4, b); }
;     }
;     __device__ __forceinline__ void unpack(const Grp& h, int bj, f32x4& v0, f32x4& v1) const {
;         if constexpr (F32IN) { v0 = h.f[2 * bj]; v1 = h.f[2 * bj + 1]; }
;         else { const u32x4 w = __builtin_bit_cast(u32x4, h.f[2 * bj]);
;             v0[0] = __uint_as_float(w.x << 16); v0[1] = __uint_as_float(w.x & 0xffff0000u); v0[2] = __uint_as_float(w.y << 16); v0[3] = __uint_as_float(w.y & 0xffff0000u);
;             v1[0] = __uint_as_float(w.z << 16); v1[1] = __uint_as_float(w.z & 0xffff0000u); v1[2] = __uint_as_float(w.w << 16); v1[3] = __uint_as_float(w.w & 0xffff0000u); }
;     }
;     __device__ __forceinline__ void operator()(const f32x4 (&acc)[2][2][4][2], const Unit& u, int wr, int wc, int fr, int fq) const {
;         Grp h[2];
;         gload(h[0], goff(u, 0, wr, wc, fr, fq));
; #pragma unroll
;         for (int g = 0; g < 8; ++g) {
;             const int ai = g >> 2, m = g & 3; const size_t off = goff(u, g, wr, wc, fr, fq);
;             if (g < 7) gload(h[(g + 1) & 1], goff(u, g + 1, wr, wc, fr, fq));
;             float sq = 0.f;
; #pragma unroll
;             for (int bj = 0; bj < 2; ++bj) { const size_t o = off + bj * HALF; f32x4 h0, h1; unpack(h[g & 1], bj, h0, h1);
;                 h0 = h0 + acc[ai][bj][m][0] * alpha; h1 = h1 + acc[ai][bj][m][1] * alpha;
;                 const u32x2 p0 = pack4(h0), p1 = pack4(h1); u32x4 w; w.x = p0.x; w.y = p0.y; w.z = p1.x; w.w = p1.y; *(u32x4*)(xa + o) = w;
;                 sq += ((h0[0] * h0[0] + h0[1] * h0[1]) + (h0[2] * h0[2] + h0[3] * h0[3])) + ((h1[0] * h1[0] + h1[1] * h1[1]) + (h1[2] * h1[2] + h1[3] * h1[3])); }
;             sq += __shfl_xor(sq, 16); sq += __shfl_xor(sq, 32);
;             if (fq == 0) ssout[(size_t)(u.pm * BM + ai * HALF + wr * 64 + m * 16 + fr) * 16 + u.pn * 4 + wc] = sq;
.LBB0_635:
	s_or_b64 exec, exec, s[40:41]
	v_or_b32_e32 v56, 32, v88
	v_ashrrev_i32_e32 v57, 31, v56
	s_waitcnt lgkmcnt(0)
	v_lshlrev_b64 v[48:49], 11, v[56:57]
	v_lshl_add_u64 v[48:49], s[22:23], 0, v[48:49]
	v_lshl_add_u64 v[48:49], s[28:29], 1, v[48:49]
	v_lshl_add_u64 v[48:49], v[48:49], 0, s[4:5]
	v_lshl_add_u64 v[58:59], v[48:49], 0, v[144:145]
	s_waitcnt vmcnt(12)
	s_waitcnt vmcnt(12)
	v_lshlrev_b32_e32 v60, 16, v232
	v_and_b32_e32 v61, 0xffff0000, v232
	v_lshlrev_b32_e32 v62, 16, v233
	v_and_b32_e32 v63, 0xffff0000, v233
	v_lshlrev_b32_e32 v68, 16, v234
	v_and_b32_e32 v69, 0xffff0000, v234
	v_lshlrev_b32_e32 v70, 16, v235
	v_and_b32_e32 v71, 0xffff0000, v235
	v_pk_add_f32 v[44:45], v[44:45], v[60:61]
	v_pk_add_f32 v[46:47], v[46:47], v[62:63]
	v_pk_add_f32 v[60:61], v[42:43], v[70:71]
	v_pk_add_f32 v[42:43], v[40:41], v[68:69]
	v_cvt_pk_bf16_f32 v40, v44, v45
	v_mul_f32_e32 v45, v45, v45
	v_fmac_f32_e32 v45, v44, v44
	v_mul_f32_e32 v44, v47, v47
	v_fmac_f32_e32 v44, v46, v46
	v_cvt_pk_bf16_f32 v41, v46, v47
	v_add_f32_e32 v44, v45, v44
	v_mul_f32_e32 v45, v43, v43
	v_mul_f32_e32 v46, v61, v61
	v_fmac_f32_e32 v45, v42, v42
	v_fmac_f32_e32 v46, v60, v60
	v_add_f32_e32 v45, v45, v46
	v_add_f32_e32 v68, v44, v45
	s_waitcnt vmcnt(12)
	v_lshlrev_b32_e32 v44, 16, v236
	v_and_b32_e32 v45, 0xffff0000, v236
	v_lshlrev_b32_e32 v46, 16, v237
	v_and_b32_e32 v47, 0xffff0000, v237
	v_lshlrev_b32_e32 v62, 16, v238
	v_and_b32_e32 v63, 0xffff0000, v238
	v_pk_add_f32 v[38:39], v[38:39], v[46:47]
	v_pk_add_f32 v[36:37], v[36:37], v[44:45]
	v_lshlrev_b32_e32 v64, 16, v239
	v_and_b32_e32 v65, 0xffff0000, v239
	v_pk_add_f32 v[46:47], v[32:33], v[62:63]
	v_mul_f32_e32 v32, v37, v37
	v_mul_f32_e32 v33, v39, v39
	v_pk_add_f32 v[44:45], v[34:35], v[64:65]
	v_fmac_f32_e32 v32, v36, v36
	v_fmac_f32_e32 v33, v38, v38
	v_add_f32_e32 v32, v32, v33
	v_mul_f32_e32 v33, v47, v47
	v_mul_f32_e32 v34, v45, v45
	v_fmac_f32_e32 v33, v46, v46
	v_fmac_f32_e32 v34, v44, v44
	v_add_f32_e32 v33, v33, v34
	v_add_f32_e32 v32, v32, v33
	v_add_f32_e32 v32, v68, v32
	ds_bpermute_b32 v33, v171, v32
	v_cvt_pk_bf16_f32 v42, v42, v43
	v_cvt_pk_bf16_f32 v43, v60, v61
	v_cvt_pk_bf16_f32 v34, v36, v37
	v_cvt_pk_bf16_f32 v35, v38, v39
	s_waitcnt lgkmcnt(0)
	v_add_f32_e32 v32, v32, v33
	ds_bpermute_b32 v33, v170, v32
	v_cvt_pk_bf16_f32 v36, v46, v47
	v_cvt_pk_bf16_f32 v37, v44, v45
	global_store_dwordx4 v[74:75], v[40:43], off
	global_store_dwordx4 v[74:75], v[34:37], off offset:256
	s_and_saveexec_b64 s[40:41], s[36:37]
	s_cbranch_execz .LBB0_637
	v_lshlrev_b64 v[34:35], 6, v[72:73]
	v_lshl_add_u64 v[34:35], s[6:7], 0, v[34:35]
	v_lshl_add_u64 v[34:35], s[18:19], 2, v[34:35]
	s_lshl_b32 s42, s54, 2
	s_mov_b32 s43, s5
	v_lshl_add_u64 v[34:35], v[34:35], 0, s[42:43]
	s_waitcnt lgkmcnt(0)
	v_add_f32_e32 v32, v32, v33
	global_store_dword v[34:35], v32, off
; __device__ __forceinline__ u32x2 pack4(f32x4 v) { u32x2 w; w.x = cvt_pk_bf16(v[0], v[1]); w.y = cvt_pk_bf16(v[2], v[3]); return w; }
;     __device__ __forceinline__ void gload(Grp& h, size_t off) const {
;         if constexpr (F32IN) { h.f[0] = *(const f32x4*)(hin + off); h.f[1] = *(const f32x4*)(hin + off + 4); h.f[2] = *(const f32x4*)(hin + off + HALF); h.f[3] = *(const f32x4*)(hin + off + HALF + 4); }
;         else { const u32x4 a = *(const u32x4*)(xa + off), b = *(const u32x4*)(xa + off + HALF); h.f[0] = __builtin_bit_cast(f32x4, a); h.f[2] = __builtin_bit_cast(f32x4, b); }
;     }
;     __device__ __forceinline__ void unpack(const Grp& h, int bj, f32x4& v0, f32x4& v1) const {
;         if constexpr (F32IN) { v0 = h.f[2 * bj]; v1 = h.f[2 * bj + 1]; }
;         else { const u32x4 w = __builtin_bit_cast(u32x4, h.f[2 * bj]);
;             v0[0] = __uint_as_float(w.x << 16); v0[1] = __uint_as_float(w.x & 0xffff0000u); v0[2] = __uint_as_float(w.y << 16); v0[3] = __uint_as_float(w.y & 0xffff0000u);
;             v1[0] = __uint_as_float(w.z << 16); v1[1] = __uint_as_float(w.z & 0xffff0000u); v1[2] = __uint_as_float(w.w << 16); v1[3] = __uint_as_float(w.w & 0xffff0000u); }
;     }
;     __device__ __forceinline__ void operator()(const f32x4 (&acc)[2][2][4][2], const Unit& u, int wr, int wc, int fr, int fq) const {
;         Grp h[2];
;         gload(h[0], goff(u, 0, wr, wc, fr, fq));
; #pragma unroll
;         for (int g = 0; g < 8; ++g) {
;             const int ai = g >> 2, m = g & 3; const size_t off = goff(u, g, wr, wc, fr, fq);
;             if (g < 7) gload(h[(g + 1) & 1], goff(u, g + 1, wr, wc, fr, fq));
;             float sq = 0.f;
; #pragma unroll
;             for (int bj = 0; bj < 2; ++bj) { const size_t o = off + bj * HALF; f32x4 h0, h1; unpack(h[g & 1], bj, h0, h1);
;                 h0 = h0 + acc[ai][bj][m][0] * alpha; h1 = h1 + acc[ai][bj][m][1] * alpha;
;                 const u32x2 p0 = pack4(h0), p1 = pack4(h1); u32x4 w; w.x = p0.x; w.y = p0.y; w.z = p1.x; w.w = p1.y; *(u32x4*)(xa + o) = w;
;                 sq += ((h0[0] * h0[0] + h0[1] * h0[1]) + (h0[2] * h0[2] + h0[3] * h0[3])) + ((h1[0] * h1[0] + h1[1] * h1[1]) + (h1[2] * h1[2] + h1[3] * h1[3])); }
;             sq += __shfl_xor(sq, 16); sq += __shfl_xor(sq, 32);
;             if (fq == 0) ssout[(size_t)(u.pm * BM + ai * HALF + wr * 64 + m * 16 + fr) * 16 + u.pn * 4 + wc] = sq;
.LBB0_637:
	s_or_b64 exec, exec, s[40:41]
	v_or_b32_e32 v40, 48, v88
	v_ashrrev_i32_e32 v41, 31, v40
	s_waitcnt lgkmcnt(0)
	v_lshlrev_b64 v[32:33], 11, v[40:41]
	v_lshl_add_u64 v[32:33], s[22:23], 0, v[32:33]
	v_lshl_add_u64 v[32:33], s[28:29], 1, v[32:33]
	v_lshl_add_u64 v[32:33], v[32:33], 0, s[4:5]
	v_lshl_add_u64 v[42:43], v[32:33], 0, v[144:145]
	global_load_dwordx4 v[36:39], v[42:43], off
	global_load_dwordx4 v[32:35], v[42:43], off offset:256
	s_waitcnt vmcnt(14)
	s_waitcnt vmcnt(14)
	v_lshlrev_b32_e32 v44, 16, v240
	v_and_b32_e32 v45, 0xffff0000, v240
	v_lshlrev_b32_e32 v46, 16, v241
	v_and_b32_e32 v47, 0xffff0000, v241
	v_lshlrev_b32_e32 v52, 16, v242
	v_and_b32_e32 v53, 0xffff0000, v242
	v_lshlrev_b32_e32 v54, 16, v243
	v_and_b32_e32 v55, 0xffff0000, v243
	v_pk_add_f32 v[28:29], v[28:29], v[44:45]
	v_pk_add_f32 v[30:31], v[30:31], v[46:47]
	v_pk_add_f32 v[44:45], v[26:27], v[54:55]
	v_pk_add_f32 v[26:27], v[24:25], v[52:53]
	v_cvt_pk_bf16_f32 v24, v28, v29
	v_mul_f32_e32 v29, v29, v29
	v_fmac_f32_e32 v29, v28, v28
	v_mul_f32_e32 v28, v31, v31
	v_fmac_f32_e32 v28, v30, v30
	v_cvt_pk_bf16_f32 v25, v30, v31
	v_add_f32_e32 v28, v29, v28
	v_mul_f32_e32 v29, v27, v27
	v_mul_f32_e32 v30, v45, v45
	v_fmac_f32_e32 v29, v26, v26
	v_fmac_f32_e32 v30, v44, v44
	v_add_f32_e32 v29, v29, v30
	v_add_f32_e32 v52, v28, v29
	s_waitcnt vmcnt(14)
	v_lshlrev_b32_e32 v28, 16, v244
	v_and_b32_e32 v29, 0xffff0000, v244
	v_lshlrev_b32_e32 v30, 16, v245
	v_and_b32_e32 v31, 0xffff0000, v245
	v_lshlrev_b32_e32 v46, 16, v246
	v_and_b32_e32 v47, 0xffff0000, v246
	v_pk_add_f32 v[22:23], v[22:23], v[30:31]
	v_pk_add_f32 v[20:21], v[20:21], v[28:29]
	v_lshlrev_b32_e32 v48, 16, v247
	v_and_b32_e32 v49, 0xffff0000, v247
	v_pk_add_f32 v[30:31], v[16:17], v[46:47]
	v_mul_f32_e32 v16, v21, v21
	v_mul_f32_e32 v17, v23, v23
	v_pk_add_f32 v[28:29], v[18:19], v[48:49]
	v_fmac_f32_e32 v16, v20, v20
	v_fmac_f32_e32 v17, v22, v22
	v_add_f32_e32 v16, v16, v17
	v_mul_f32_e32 v17, v31, v31
	v_mul_f32_e32 v18, v29, v29
	v_fmac_f32_e32 v17, v30, v30
	v_fmac_f32_e32 v18, v28, v28
	v_add_f32_e32 v17, v17, v18
	v_add_f32_e32 v16, v16, v17
	v_add_f32_e32 v16, v52, v16
	ds_bpermute_b32 v17, v171, v16
	v_cvt_pk_bf16_f32 v26, v26, v27
	v_cvt_pk_bf16_f32 v27, v44, v45
	v_cvt_pk_bf16_f32 v18, v20, v21
	v_cvt_pk_bf16_f32 v19, v22, v23
	s_waitcnt lgkmcnt(0)
	v_add_f32_e32 v16, v16, v17
	ds_bpermute_b32 v17, v170, v16
	v_cvt_pk_bf16_f32 v20, v30, v31
	v_cvt_pk_bf16_f32 v21, v28, v29
	global_store_dwordx4 v[58:59], v[24:27], off
	global_store_dwordx4 v[58:59], v[18:21], off offset:256
	s_and_saveexec_b64 s[28:29], s[36:37]
	s_cbranch_execz .LBB0_639
	v_lshlrev_b64 v[18:19], 6, v[56:57]
	v_lshl_add_u64 v[18:19], s[6:7], 0, v[18:19]
	v_lshl_add_u64 v[18:19], s[18:19], 2, v[18:19]
	s_lshl_b32 s4, s54, 2
	v_lshl_add_u64 v[18:19], v[18:19], 0, s[4:5]
	s_waitcnt lgkmcnt(0)
	v_add_f32_e32 v16, v16, v17
	global_store_dword v[18:19], v16, off
.LBB0_639:
	s_or_b64 exec, exec, s[28:29]
	s_waitcnt vmcnt(2)
	v_lshlrev_b32_e32 v16, 16, v36
	s_waitcnt lgkmcnt(0)
	v_and_b32_e32 v17, 0xffff0000, v36
	v_lshlrev_b32_e32 v18, 16, v37
	v_and_b32_e32 v19, 0xffff0000, v37
	v_lshlrev_b32_e32 v20, 16, v38
	v_and_b32_e32 v21, 0xffff0000, v38
	v_lshlrev_b32_e32 v22, 16, v39
	v_and_b32_e32 v23, 0xffff0000, v39
	v_pk_add_f32 v[12:13], v[12:13], v[16:17]
	v_pk_add_f32 v[14:15], v[14:15], v[18:19]
	v_pk_add_f32 v[16:17], v[10:11], v[22:23]
	v_pk_add_f32 v[10:11], v[8:9], v[20:21]
	v_cvt_pk_bf16_f32 v8, v12, v13
	v_mul_f32_e32 v13, v13, v13
	v_fmac_f32_e32 v13, v12, v12
	v_mul_f32_e32 v12, v15, v15
	v_fmac_f32_e32 v12, v14, v14
	v_cvt_pk_bf16_f32 v9, v14, v15
	v_add_f32_e32 v12, v13, v12
	v_mul_f32_e32 v13, v11, v11
	v_mul_f32_e32 v14, v17, v17
	v_fmac_f32_e32 v13, v10, v10
	v_fmac_f32_e32 v14, v16, v16
	v_add_f32_e32 v13, v13, v14
	v_add_f32_e32 v22, v12, v13
	s_waitcnt vmcnt(2)
	v_lshlrev_b32_e32 v12, 16, v32
	v_and_b32_e32 v13, 0xffff0000, v32
	v_lshlrev_b32_e32 v14, 16, v33
	v_and_b32_e32 v15, 0xffff0000, v33
	v_lshlrev_b32_e32 v18, 16, v34
	v_and_b32_e32 v19, 0xffff0000, v34
	v_pk_add_f32 v[6:7], v[6:7], v[14:15]
	v_pk_add_f32 v[4:5], v[4:5], v[12:13]
	v_lshlrev_b32_e32 v20, 16, v35
	v_and_b32_e32 v21, 0xffff0000, v35
	v_pk_add_f32 v[14:15], v[0:1], v[18:19]
	v_mul_f32_e32 v0, v5, v5
	v_mul_f32_e32 v1, v7, v7
	v_pk_add_f32 v[12:13], v[2:3], v[20:21]
	v_fmac_f32_e32 v0, v4, v4
	v_fmac_f32_e32 v1, v6, v6
	v_add_f32_e32 v0, v0, v1
	v_mul_f32_e32 v1, v15, v15
	v_mul_f32_e32 v2, v13, v13
	v_fmac_f32_e32 v1, v14, v14
	v_fmac_f32_e32 v2, v12, v12
	v_add_f32_e32 v1, v1, v2
	v_add_f32_e32 v0, v0, v1
	v_add_f32_e32 v0, v22, v0
	ds_bpermute_b32 v1, v171, v0
	v_cvt_pk_bf16_f32 v10, v10, v11
	v_cvt_pk_bf16_f32 v11, v16, v17
	v_cvt_pk_bf16_f32 v2, v4, v5
	s_waitcnt lgkmcnt(0)
	v_add_f32_e32 v0, v0, v1
	ds_bpermute_b32 v1, v170, v0
	v_cvt_pk_bf16_f32 v3, v6, v7
	v_cvt_pk_bf16_f32 v4, v14, v15
	v_cvt_pk_bf16_f32 v5, v12, v13
	global_store_dwordx4 v[42:43], v[8:11], off
	global_store_dwordx4 v[42:43], v[2:5], off offset:256
	s_and_saveexec_b64 s[28:29], s[36:37]
	s_cbranch_execz .LBB0_641
	v_lshlrev_b64 v[2:3], 6, v[40:41]
	v_lshl_add_u64 v[2:3], s[6:7], 0, v[2:3]
	v_lshl_add_u64 v[2:3], s[18:19], 2, v[2:3]
	s_lshl_b32 s4, s54, 2
	v_lshl_add_u64 v[2:3], v[2:3], 0, s[4:5]
	s_waitcnt lgkmcnt(0)
	v_add_f32_e32 v0, v0, v1
	global_store_dword v[2:3], v0, off

; __device__ __forceinline__ u32x2 pack4(f32x4 v) { u32x2 w; w.x = cvt_pk_bf16(v[0], v[1]); w.y = cvt_pk_bf16(v[2], v[3]); return w; }
;     __device__ __forceinline__ size_t goff(const Unit& u, int g, int wr, int wc, int fr, int fq) const { return (size_t)(u.pm * BM + (g >> 2) * HALF + wr * 64 + (g & 3) * 16 + fr) * 1024 + u.pn * BM + wc * 32 + fq * 8; }
;     __device__ __forceinline__ void gload(Grp& h, size_t off) const {
;         if constexpr (F32IN) { h.f[0] = *(const f32x4*)(hin + off); h.f[1] = *(const f32x4*)(hin + off + 4); h.f[2] = *(const f32x4*)(hin + off + HALF); h.f[3] = *(const f32x4*)(hin + off + HALF + 4); }
;         else { const u32x4 a = *(const u32x4*)(xa + off), b = *(const u32x4*)(xa + off + HALF); h.f[0] = __builtin_bit_cast(f32x4, a); h.f[2] = __builtin_bit_cast(f32x4, b); }
;     }
;     __device__ __forceinline__ void unpack(const Grp& h, int bj, f32x4& v0, f32x4& v1) const {
;         if constexpr (F32IN) { v0 = h.f[2 * bj]; v1 = h.f[2 * bj + 1]; }
;         else { const u32x4 w = __builtin_bit_cast(u32x4, h.f[2 * bj]);
;             v0[0] = __uint_as_float(w.x << 16); v0[1] = __uint_as_float(w.x & 0xffff0000u); v0[2] = __uint_as_float(w.y << 16); v0[3] = __uint_as_float(w.y & 0xffff0000u);
;             v1[0] = __uint_as_float(w.z << 16); v1[1] = __uint_as_float(w.z & 0xffff0000u); v1[2] = __uint_as_float(w.w << 16); v1[3] = __uint_as_float(w.w & 0xffff0000u); }
;     }
;     __device__ __forceinline__ void operator()(const f32x4 (&acc)[2][2][4][2], const Unit& u, int wr, int wc, int fr, int fq) const {
;         Grp h[2];
;         gload(h[0], goff(u, 0, wr, wc, fr, fq));
; #pragma unroll
;         for (int g = 0; g < 8; ++g) {
;             const int ai = g >> 2, m = g & 3; const size_t off = goff(u, g, wr, wc, fr, fq);
;             if (g < 7) gload(h[(g + 1) & 1], goff(u, g + 1, wr, wc, fr, fq));
;             float sq = 0.f;
; #pragma unroll
;             for (int bj = 0; bj < 2; ++bj) { const size_t o = off + bj * HALF; f32x4 h0, h1; unpack(h[g & 1], bj, h0, h1);
;                 h0 = h0 + acc[ai][bj][m][0] * alpha; h1 = h1 + acc[ai][bj][m][1] * alpha;
;                 const u32x2 p0 = pack4(h0), p1 = pack4(h1); u32x4 w; w.x = p0.x; w.y = p0.y; w.z = p1.x; w.w = p1.y; *(u32x4*)(xa + o) = w;
.LBB0_860:
	v_lshl_add_u32 v162, s4, 8, v157
	v_ashrrev_i32_e32 v163, 31, v162
	s_lshl_b32 s18, s58, 8
	s_ashr_i32 s19, s18, 31
	v_lshlrev_b64 v[128:129], 11, v[162:163]
	v_lshl_add_u64 v[128:129], s[22:23], 0, v[128:129]
	s_lshl_b64 s[16:17], s[18:19], 1
	v_lshl_add_u64 v[128:129], v[128:129], 0, s[16:17]
	s_lshl_b32 s4, s51, 1
	v_lshl_add_u64 v[128:129], v[128:129], 0, s[4:5]
	v_lshlrev_b32_e32 v144, 1, v156
	v_lshl_add_u64 v[180:181], v[128:129], 0, v[144:145]
	global_load_dwordx4 v[172:175], v[180:181], off
	global_load_dwordx4 v[176:179], v[180:181], off offset:256
	v_or_b32_e32 v164, 16, v162
	v_ashrrev_i32_e32 v165, 31, v164
	v_lshlrev_b64 v[128:129], 11, v[164:165]
	v_lshl_add_u64 v[128:129], s[22:23], 0, v[128:129]
	v_lshl_add_u64 v[128:129], v[128:129], 0, s[16:17]
	v_lshl_add_u64 v[128:129], v[128:129], 0, s[4:5]
	v_lshl_add_u64 v[166:167], v[128:129], 0, v[144:145]
	global_load_dwordx4 v[132:135], v[166:167], off
	global_load_dwordx4 v[128:131], v[166:167], off offset:256
	v_add_co_u32_e32 v182, vcc, 0x10000, v180
	s_nop 1
	v_addc_co_u32_e32 v183, vcc, 0, v181, vcc
	global_load_dwordx4 v[190:193], v[182:183], off
	global_load_dwordx4 v[194:197], v[182:183], off offset:256
	v_add_co_u32_e32 v182, vcc, 0x18000, v180
	s_nop 1
	v_addc_co_u32_e32 v183, vcc, 0, v181, vcc
	global_load_dwordx4 v[216:219], v[182:183], off
	global_load_dwordx4 v[220:223], v[182:183], off offset:256
	v_add_co_u32_e32 v182, vcc, 0x40000, v180
	s_nop 1
	v_addc_co_u32_e32 v183, vcc, 0, v181, vcc
	global_load_dwordx4 v[224:227], v[182:183], off
	global_load_dwordx4 v[228:231], v[182:183], off offset:256
	v_add_co_u32_e32 v182, vcc, 0x48000, v180
	s_nop 1
	v_addc_co_u32_e32 v183, vcc, 0, v181, vcc
	global_load_dwordx4 v[232:235], v[182:183], off
	global_load_dwordx4 v[236:239], v[182:183], off offset:256
	v_add_co_u32_e32 v182, vcc, 0x50000, v180
	s_nop 1
	v_addc_co_u32_e32 v183, vcc, 0, v181, vcc
	global_load_dwordx4 v[240:243], v[182:183], off
	global_load_dwordx4 v[244:247], v[182:183], off offset:256
	v_and_b32_e32 v171, 64, v203
	v_xor_b32_e32 v170, 16, v203
	v_add_u32_e32 v171, 64, v171
	v_xor_b32_e32 v182, 32, v203
	v_cmp_lt_i32_e32 vcc, v170, v171
	s_lshl_b32 s16, s58, 2
	s_ashr_i32 s17, s16, 31
	v_cndmask_b32_e32 v170, v203, v170, vcc
	v_cmp_lt_i32_e32 vcc, v182, v171
	v_lshlrev_b32_e32 v171, 2, v170
	s_waitcnt vmcnt(12)
	v_and_b32_e32 v183, 0xffff0000, v172
	v_cndmask_b32_e32 v182, v203, v182, vcc
	v_lshlrev_b32_e32 v170, 2, v182
	v_lshlrev_b32_e32 v182, 16, v172
	v_lshlrev_b32_e32 v172, 16, v173
	v_and_b32_e32 v173, 0xffff0000, v173
	v_lshlrev_b32_e32 v184, 16, v174
	v_and_b32_e32 v185, 0xffff0000, v174
	v_lshlrev_b32_e32 v174, 16, v175
	v_and_b32_e32 v175, 0xffff0000, v175
	v_lshlrev_b32_e32 v186, 16, v176
	v_and_b32_e32 v187, 0xffff0000, v176
	v_lshlrev_b32_e32 v176, 16, v177
	v_and_b32_e32 v177, 0xffff0000, v177
	v_lshlrev_b32_e32 v188, 16, v178
	v_and_b32_e32 v189, 0xffff0000, v178
	v_lshlrev_b32_e32 v178, 16, v179
	v_and_b32_e32 v179, 0xffff0000, v179
	v_pk_fma_f32 v[126:127], v[126:127], 0.5, v[172:173] op_sel_hi:[1,0,1]
	v_pk_fma_f32 v[124:125], v[124:125], 0.5, v[182:183] op_sel_hi:[1,0,1]
	v_pk_fma_f32 v[122:123], v[122:123], 0.5, v[174:175] op_sel_hi:[1,0,1]
	v_pk_fma_f32 v[120:121], v[120:121], 0.5, v[184:185] op_sel_hi:[1,0,1]
	v_pk_fma_f32 v[118:119], v[118:119], 0.5, v[176:177] op_sel_hi:[1,0,1]
	v_pk_fma_f32 v[116:117], v[116:117], 0.5, v[186:187] op_sel_hi:[1,0,1]
	v_pk_fma_f32 v[172:173], v[114:115], 0.5, v[178:179] op_sel_hi:[1,0,1]
	v_pk_fma_f32 v[174:175], v[112:113], 0.5, v[188:189] op_sel_hi:[1,0,1]
	v_cvt_pk_bf16_f32 v112, v124, v125
	v_cvt_pk_bf16_f32 v113, v126, v127
	v_mul_f32_e32 v114, v125, v125
	v_mul_f32_e32 v115, v127, v127
	v_mul_f32_e32 v125, v121, v121
	v_mul_f32_e32 v127, v123, v123
	v_mul_f32_e32 v176, v117, v117
	v_mul_f32_e32 v177, v119, v119
	v_mul_f32_e32 v178, v175, v175
	v_mul_f32_e32 v179, v173, v173
	v_fmac_f32_e32 v114, v124, v124
	v_fmac_f32_e32 v115, v126, v126
	v_fmac_f32_e32 v125, v120, v120
	v_fmac_f32_e32 v127, v122, v122
	v_fmac_f32_e32 v176, v116, v116
	v_fmac_f32_e32 v177, v118, v118
	v_fmac_f32_e32 v178, v174, v174
	v_fmac_f32_e32 v179, v172, v172
	v_add_f32_e32 v114, v114, v115
	v_add_f32_e32 v115, v125, v127
	v_add_f32_e32 v124, v176, v177
	v_add_f32_e32 v125, v178, v179
	v_add_f32_e32 v114, v114, v115
	v_add_f32_e32 v115, v124, v125
	v_add_f32_e32 v124, v114, v115
	ds_bpermute_b32 v125, v171, v124
	v_cvt_pk_bf16_f32 v114, v120, v121
	v_cvt_pk_bf16_f32 v115, v122, v123
	global_store_dwordx4 v[180:181], v[112:115], off
	s_waitcnt lgkmcnt(0)
	s_nop 0
	v_add_f32_e32 v112, v124, v125
	ds_bpermute_b32 v113, v170, v112
	v_cvt_pk_bf16_f32 v114, v116, v117
	v_cvt_pk_bf16_f32 v115, v118, v119
	v_cvt_pk_bf16_f32 v116, v174, v175
	v_cvt_pk_bf16_f32 v117, v172, v173
	global_store_dwordx4 v[180:181], v[114:117], off offset:256
	s_and_saveexec_b64 s[28:29], s[36:37]
	s_cbranch_execz .LBB0_862
	v_lshlrev_b64 v[114:115], 6, v[162:163]
	v_lshl_add_u64 v[114:115], s[24:25], 0, v[114:115]
	v_lshl_add_u64 v[114:115], s[16:17], 2, v[114:115]
	s_lshl_b32 s40, s50, 2
	s_mov_b32 s41, s5
	v_lshl_add_u64 v[114:115], v[114:115], 0, s[40:41]
	s_waitcnt lgkmcnt(0)
	v_add_f32_e32 v112, v112, v113
	global_store_dword v[114:115], v112, off
; __device__ __forceinline__ u32x2 pack4(f32x4 v) { u32x2 w; w.x = cvt_pk_bf16(v[0], v[1]); w.y = cvt_pk_bf16(v[2], v[3]); return w; }
;     __device__ __forceinline__ void gload(Grp& h, size_t off) const {
;         if constexpr (F32IN) { h.f[0] = *(const f32x4*)(hin + off); h.f[1] = *(const f32x4*)(hin + off + 4); h.f[2] = *(const f32x4*)(hin + off + HALF); h.f[3] = *(const f32x4*)(hin + off + HALF + 4); }
;         else { const u32x4 a = *(const u32x4*)(xa + off), b = *(const u32x4*)(xa + off + HALF); h.f[0] = __builtin_bit_cast(f32x4, a); h.f[2] = __builtin_bit_cast(f32x4, b); }
;     }
;     __device__ __forceinline__ void unpack(const Grp& h, int bj, f32x4& v0, f32x4& v1) const {
;         if constexpr (F32IN) { v0 = h.f[2 * bj]; v1 = h.f[2 * bj + 1]; }
;         else { const u32x4 w = __builtin_bit_cast(u32x4, h.f[2 * bj]);
;             v0[0] = __uint_as_float(w.x << 16); v0[1] = __uint_as_float(w.x & 0xffff0000u); v0[2] = __uint_as_float(w.y << 16); v0[3] = __uint_as_float(w.y & 0xffff0000u);
;             v1[0] = __uint_as_float(w.z << 16); v1[1] = __uint_as_float(w.z & 0xffff0000u); v1[2] = __uint_as_float(w.w << 16); v1[3] = __uint_as_float(w.w & 0xffff0000u); }
;     }
;     __device__ __forceinline__ void operator()(const f32x4 (&acc)[2][2][4][2], const Unit& u, int wr, int wc, int fr, int fq) const {
;         Grp h[2];
;         gload(h[0], goff(u, 0, wr, wc, fr, fq));
; #pragma unroll
;         for (int g = 0; g < 8; ++g) {
;             const int ai = g >> 2, m = g & 3; const size_t off = goff(u, g, wr, wc, fr, fq);
;             if (g < 7) gload(h[(g + 1) & 1], goff(u, g + 1, wr, wc, fr, fq));
;             float sq = 0.f;
; #pragma unroll
;             for (int bj = 0; bj < 2; ++bj) { const size_t o = off + bj * HALF; f32x4 h0, h1; unpack(h[g & 1], bj, h0, h1);
;                 h0 = h0 + acc[ai][bj][m][0] * alpha; h1 = h1 + acc[ai][bj][m][1] * alpha;
;                 const u32x2 p0 = pack4(h0), p1 = pack4(h1); u32x4 w; w.x = p0.x; w.y = p0.y; w.z = p1.x; w.w = p1.y; *(u32x4*)(xa + o) = w;
;                 sq += ((h0[0] * h0[0] + h0[1] * h0[1]) + (h0[2] * h0[2] + h0[3] * h0[3])) + ((h1[0] * h1[0] + h1[1] * h1[1]) + (h1[2] * h1[2] + h1[3] * h1[3])); }
;             sq += __shfl_xor(sq, 16); sq += __shfl_xor(sq, 32);
;             if (fq == 0) ssout[(size_t)(u.pm * BM + ai * HALF + wr * 64 + m * 16 + fr) * 16 + u.pn * 4 + wc] = sq;
.LBB0_862:
	s_or_b64 exec, exec, s[28:29]
	v_or_b32_e32 v120, 32, v162
	v_ashrrev_i32_e32 v121, 31, v120
	s_waitcnt lgkmcnt(0)
	v_lshlrev_b64 v[112:113], 11, v[120:121]
	v_lshl_add_u64 v[112:113], s[22:23], 0, v[112:113]
	v_lshl_add_u64 v[112:113], s[18:19], 1, v[112:113]
	v_lshl_add_u64 v[112:113], v[112:113], 0, s[4:5]
	v_lshl_add_u64 v[122:123], v[112:113], 0, v[144:145]
	s_waitcnt vmcnt(12)
	v_lshlrev_b32_e32 v124, 16, v132
	v_and_b32_e32 v125, 0xffff0000, v132
	v_lshlrev_b32_e32 v126, 16, v133
	v_and_b32_e32 v127, 0xffff0000, v133
	v_lshlrev_b32_e32 v132, 16, v134
	v_and_b32_e32 v133, 0xffff0000, v134
	v_lshlrev_b32_e32 v134, 16, v135
	v_and_b32_e32 v135, 0xffff0000, v135
	v_pk_fma_f32 v[108:109], v[108:109], 0.5, v[124:125] op_sel_hi:[1,0,1]
	v_pk_fma_f32 v[110:111], v[110:111], 0.5, v[126:127] op_sel_hi:[1,0,1]
	v_pk_fma_f32 v[124:125], v[106:107], 0.5, v[134:135] op_sel_hi:[1,0,1]
	v_pk_fma_f32 v[106:107], v[104:105], 0.5, v[132:133] op_sel_hi:[1,0,1]
	v_cvt_pk_bf16_f32 v104, v108, v109
	v_mul_f32_e32 v109, v109, v109
	v_fmac_f32_e32 v109, v108, v108
	v_mul_f32_e32 v108, v111, v111
	v_fmac_f32_e32 v108, v110, v110
	v_cvt_pk_bf16_f32 v105, v110, v111
	v_add_f32_e32 v108, v109, v108
	v_mul_f32_e32 v109, v107, v107
	v_mul_f32_e32 v110, v125, v125
	v_fmac_f32_e32 v109, v106, v106
	v_fmac_f32_e32 v110, v124, v124
	v_add_f32_e32 v109, v109, v110
	v_add_f32_e32 v132, v108, v109
	v_lshlrev_b32_e32 v108, 16, v128
	v_and_b32_e32 v109, 0xffff0000, v128
	v_lshlrev_b32_e32 v110, 16, v129
	v_and_b32_e32 v111, 0xffff0000, v129
	v_lshlrev_b32_e32 v126, 16, v130
	v_and_b32_e32 v127, 0xffff0000, v130
	v_pk_fma_f32 v[102:103], v[102:103], 0.5, v[110:111] op_sel_hi:[1,0,1]
	v_pk_fma_f32 v[100:101], v[100:101], 0.5, v[108:109] op_sel_hi:[1,0,1]
	v_lshlrev_b32_e32 v128, 16, v131
	v_and_b32_e32 v129, 0xffff0000, v131
	v_pk_fma_f32 v[110:111], v[96:97], 0.5, v[126:127] op_sel_hi:[1,0,1]
	v_mul_f32_e32 v96, v101, v101
	v_mul_f32_e32 v97, v103, v103
	v_pk_fma_f32 v[108:109], v[98:99], 0.5, v[128:129] op_sel_hi:[1,0,1]
	v_fmac_f32_e32 v96, v100, v100
	v_fmac_f32_e32 v97, v102, v102
	v_add_f32_e32 v96, v96, v97
	v_mul_f32_e32 v97, v111, v111
	v_mul_f32_e32 v98, v109, v109
	v_fmac_f32_e32 v97, v110, v110
	v_fmac_f32_e32 v98, v108, v108
	v_add_f32_e32 v97, v97, v98
	v_add_f32_e32 v96, v96, v97
	v_add_f32_e32 v96, v132, v96
	ds_bpermute_b32 v97, v171, v96
	v_cvt_pk_bf16_f32 v106, v106, v107
	v_cvt_pk_bf16_f32 v107, v124, v125
	v_cvt_pk_bf16_f32 v98, v100, v101
	v_cvt_pk_bf16_f32 v99, v102, v103
	s_waitcnt lgkmcnt(0)
	v_add_f32_e32 v96, v96, v97
	ds_bpermute_b32 v97, v170, v96
	v_cvt_pk_bf16_f32 v100, v110, v111
	v_cvt_pk_bf16_f32 v101, v108, v109
	global_store_dwordx4 v[166:167], v[104:107], off
	global_store_dwordx4 v[166:167], v[98:101], off offset:256
	s_and_saveexec_b64 s[28:29], s[36:37]
	s_cbranch_execz .LBB0_864
	v_lshlrev_b64 v[98:99], 6, v[164:165]
	v_lshl_add_u64 v[98:99], s[24:25], 0, v[98:99]
	v_lshl_add_u64 v[98:99], s[16:17], 2, v[98:99]
	s_lshl_b32 s40, s50, 2
	s_mov_b32 s41, s5
	v_lshl_add_u64 v[98:99], v[98:99], 0, s[40:41]
	s_waitcnt lgkmcnt(0)
	v_add_f32_e32 v96, v96, v97
	global_store_dword v[98:99], v96, off
.LBB0_864:
	s_or_b64 exec, exec, s[28:29]
	v_or_b32_e32 v104, 48, v162
	v_ashrrev_i32_e32 v105, 31, v104
	s_waitcnt lgkmcnt(0)
	v_lshlrev_b64 v[96:97], 11, v[104:105]
	v_lshl_add_u64 v[96:97], s[22:23], 0, v[96:97]
	v_lshl_add_u64 v[96:97], s[18:19], 1, v[96:97]
	v_lshl_add_u64 v[96:97], v[96:97], 0, s[4:5]
	v_lshl_add_u64 v[106:107], v[96:97], 0, v[144:145]
	s_waitcnt vmcnt(12)
	s_waitcnt vmcnt(12)
	v_lshlrev_b32_e32 v108, 16, v190
	v_and_b32_e32 v109, 0xffff0000, v190
	v_lshlrev_b32_e32 v110, 16, v191
	v_and_b32_e32 v111, 0xffff0000, v191
	v_lshlrev_b32_e32 v116, 16, v192
	v_and_b32_e32 v117, 0xffff0000, v192
	v_lshlrev_b32_e32 v118, 16, v193
	v_and_b32_e32 v119, 0xffff0000, v193
	v_pk_fma_f32 v[92:93], v[92:93], 0.5, v[108:109] op_sel_hi:[1,0,1]
	v_pk_fma_f32 v[94:95], v[94:95], 0.5, v[110:111] op_sel_hi:[1,0,1]
	v_pk_fma_f32 v[108:109], v[90:91], 0.5, v[118:119] op_sel_hi:[1,0,1]
	v_pk_fma_f32 v[90:91], v[88:89], 0.5, v[116:117] op_sel_hi:[1,0,1]
	v_cvt_pk_bf16_f32 v88, v92, v93
	v_mul_f32_e32 v93, v93, v93
	v_fmac_f32_e32 v93, v92, v92
	v_mul_f32_e32 v92, v95, v95
	v_fmac_f32_e32 v92, v94, v94
	v_cvt_pk_bf16_f32 v89, v94, v95
	v_add_f32_e32 v92, v93, v92
	v_mul_f32_e32 v93, v91, v91
	v_mul_f32_e32 v94, v109, v109
	v_fmac_f32_e32 v93, v90, v90
	v_fmac_f32_e32 v94, v108, v108
	v_add_f32_e32 v93, v93, v94
	v_add_f32_e32 v116, v92, v93
	s_waitcnt vmcnt(12)
	v_lshlrev_b32_e32 v92, 16, v194
	v_and_b32_e32 v93, 0xffff0000, v194
	v_lshlrev_b32_e32 v94, 16, v195
	v_and_b32_e32 v95, 0xffff0000, v195
	v_lshlrev_b32_e32 v110, 16, v196
	v_and_b32_e32 v111, 0xffff0000, v196
	v_pk_fma_f32 v[86:87], v[86:87], 0.5, v[94:95] op_sel_hi:[1,0,1]
	v_pk_fma_f32 v[84:85], v[84:85], 0.5, v[92:93] op_sel_hi:[1,0,1]
	v_lshlrev_b32_e32 v112, 16, v197
	v_and_b32_e32 v113, 0xffff0000, v197
	v_pk_fma_f32 v[94:95], v[80:81], 0.5, v[110:111] op_sel_hi:[1,0,1]
	v_mul_f32_e32 v80, v85, v85
	v_mul_f32_e32 v81, v87, v87
	v_pk_fma_f32 v[92:93], v[82:83], 0.5, v[112:113] op_sel_hi:[1,0,1]
	v_fmac_f32_e32 v80, v84, v84
	v_fmac_f32_e32 v81, v86, v86
	v_add_f32_e32 v80, v80, v81
	v_mul_f32_e32 v81, v95, v95
	v_mul_f32_e32 v82, v93, v93
	v_fmac_f32_e32 v81, v94, v94
	v_fmac_f32_e32 v82, v92, v92
	v_add_f32_e32 v81, v81, v82
	v_add_f32_e32 v80, v80, v81
	v_add_f32_e32 v80, v116, v80
	ds_bpermute_b32 v81, v171, v80
	v_cvt_pk_bf16_f32 v90, v90, v91
	v_cvt_pk_bf16_f32 v91, v108, v109
	v_cvt_pk_bf16_f32 v82, v84, v85
	v_cvt_pk_bf16_f32 v83, v86, v87
	s_waitcnt lgkmcnt(0)
	v_add_f32_e32 v80, v80, v81
	ds_bpermute_b32 v81, v170, v80
	v_cvt_pk_bf16_f32 v84, v94, v95
	v_cvt_pk_bf16_f32 v85, v92, v93
	global_store_dwordx4 v[122:123], v[88:91], off
	global_store_dwordx4 v[122:123], v[82:85], off offset:256
	s_and_saveexec_b64 s[28:29], s[36:37]
	s_cbranch_execz .LBB0_866
	v_lshlrev_b64 v[82:83], 6, v[120:121]
	v_lshl_add_u64 v[82:83], s[24:25], 0, v[82:83]
	v_lshl_add_u64 v[82:83], s[16:17], 2, v[82:83]
	s_lshl_b32 s40, s50, 2
	s_mov_b32 s41, s5
	v_lshl_add_u64 v[82:83], v[82:83], 0, s[40:41]
	s_waitcnt lgkmcnt(0)
	v_add_f32_e32 v80, v80, v81
	global_store_dword v[82:83], v80, off
; __device__ __forceinline__ u32x2 pack4(f32x4 v) { u32x2 w; w.x = cvt_pk_bf16(v[0], v[1]); w.y = cvt_pk_bf16(v[2], v[3]); return w; }
;     __device__ __forceinline__ void gload(Grp& h, size_t off) const {
;         if constexpr (F32IN) { h.f[0] = *(const f32x4*)(hin + off); h.f[1] = *(const f32x4*)(hin + off + 4); h.f[2] = *(const f32x4*)(hin + off + HALF); h.f[3] = *(const f32x4*)(hin + off + HALF + 4); }
;         else { const u32x4 a = *(const u32x4*)(xa + off), b = *(const u32x4*)(xa + off + HALF); h.f[0] = __builtin_bit_cast(f32x4, a); h.f[2] = __builtin_bit_cast(f32x4, b); }
;     }
;     __device__ __forceinline__ void unpack(const Grp& h, int bj, f32x4& v0, f32x4& v1) const {
;         if constexpr (F32IN) { v0 = h.f[2 * bj]; v1 = h.f[2 * bj + 1]; }
;         else { const u32x4 w = __builtin_bit_cast(u32x4, h.f[2 * bj]);
;             v0[0] = __uint_as_float(w.x << 16); v0[1] = __uint_as_float(w.x & 0xffff0000u); v0[2] = __uint_as_float(w.y << 16); v0[3] = __uint_as_float(w.y & 0xffff0000u);
;             v1[0] = __uint_as_float(w.z << 16); v1[1] = __uint_as_float(w.z & 0xffff0000u); v1[2] = __uint_as_float(w.w << 16); v1[3] = __uint_as_float(w.w & 0xffff0000u); }
;     }
;     __device__ __forceinline__ void operator()(const f32x4 (&acc)[2][2][4][2], const Unit& u, int wr, int wc, int fr, int fq) const {
;         Grp h[2];
;         gload(h[0], goff(u, 0, wr, wc, fr, fq));
; #pragma unroll
;         for (int g = 0; g < 8; ++g) {
;             const int ai = g >> 2, m = g & 3; const size_t off = goff(u, g, wr, wc, fr, fq);
;             if (g < 7) gload(h[(g + 1) & 1], goff(u, g + 1, wr, wc, fr, fq));
;             float sq = 0.f;
; #pragma unroll
;             for (int bj = 0; bj < 2; ++bj) { const size_t o = off + bj * HALF; f32x4 h0, h1; unpack(h[g & 1], bj, h0, h1);
;                 h0 = h0 + acc[ai][bj][m][0] * alpha; h1 = h1 + acc[ai][bj][m][1] * alpha;
;                 const u32x2 p0 = pack4(h0), p1 = pack4(h1); u32x4 w; w.x = p0.x; w.y = p0.y; w.z = p1.x; w.w = p1.y; *(u32x4*)(xa + o) = w;
;                 sq += ((h0[0] * h0[0] + h0[1] * h0[1]) + (h0[2] * h0[2] + h0[3] * h0[3])) + ((h1[0] * h1[0] + h1[1] * h1[1]) + (h1[2] * h1[2] + h1[3] * h1[3])); }
;             sq += __shfl_xor(sq, 16); sq += __shfl_xor(sq, 32);
;             if (fq == 0) ssout[(size_t)(u.pm * BM + ai * HALF + wr * 64 + m * 16 + fr) * 16 + u.pn * 4 + wc] = sq;
.LBB0_866:
	s_or_b64 exec, exec, s[28:29]
	v_add_u32_e32 v88, 0x80, v162
	v_ashrrev_i32_e32 v89, 31, v88
	s_waitcnt lgkmcnt(0)
	v_lshlrev_b64 v[80:81], 11, v[88:89]
	v_lshl_add_u64 v[80:81], s[22:23], 0, v[80:81]
	v_lshl_add_u64 v[80:81], s[18:19], 1, v[80:81]
	v_lshl_add_u64 v[80:81], v[80:81], 0, s[4:5]
	v_lshl_add_u64 v[90:91], v[80:81], 0, v[144:145]
	s_waitcnt vmcnt(12)
	s_waitcnt vmcnt(12)
	v_lshlrev_b32_e32 v92, 16, v216
	v_and_b32_e32 v93, 0xffff0000, v216
	v_lshlrev_b32_e32 v94, 16, v217
	v_and_b32_e32 v95, 0xffff0000, v217
	v_lshlrev_b32_e32 v100, 16, v218
	v_and_b32_e32 v101, 0xffff0000, v218
	v_lshlrev_b32_e32 v102, 16, v219
	v_and_b32_e32 v103, 0xffff0000, v219
	v_pk_fma_f32 v[76:77], v[76:77], 0.5, v[92:93] op_sel_hi:[1,0,1]
	v_pk_fma_f32 v[78:79], v[78:79], 0.5, v[94:95] op_sel_hi:[1,0,1]
	v_pk_fma_f32 v[92:93], v[74:75], 0.5, v[102:103] op_sel_hi:[1,0,1]
	v_pk_fma_f32 v[74:75], v[72:73], 0.5, v[100:101] op_sel_hi:[1,0,1]
	v_cvt_pk_bf16_f32 v72, v76, v77
	v_mul_f32_e32 v77, v77, v77
	v_fmac_f32_e32 v77, v76, v76
	v_mul_f32_e32 v76, v79, v79
	v_fmac_f32_e32 v76, v78, v78
	v_cvt_pk_bf16_f32 v73, v78, v79
	v_add_f32_e32 v76, v77, v76
	v_mul_f32_e32 v77, v75, v75
	v_mul_f32_e32 v78, v93, v93
	v_fmac_f32_e32 v77, v74, v74
	v_fmac_f32_e32 v78, v92, v92
	v_add_f32_e32 v77, v77, v78
	v_add_f32_e32 v100, v76, v77
	s_waitcnt vmcnt(12)
	v_lshlrev_b32_e32 v76, 16, v220
	v_and_b32_e32 v77, 0xffff0000, v220
	v_lshlrev_b32_e32 v78, 16, v221
	v_and_b32_e32 v79, 0xffff0000, v221
	v_lshlrev_b32_e32 v94, 16, v222
	v_and_b32_e32 v95, 0xffff0000, v222
	v_pk_fma_f32 v[70:71], v[70:71], 0.5, v[78:79] op_sel_hi:[1,0,1]
	v_pk_fma_f32 v[68:69], v[68:69], 0.5, v[76:77] op_sel_hi:[1,0,1]
	v_lshlrev_b32_e32 v96, 16, v223
	v_and_b32_e32 v97, 0xffff0000, v223
	v_pk_fma_f32 v[78:79], v[64:65], 0.5, v[94:95] op_sel_hi:[1,0,1]
	v_mul_f32_e32 v64, v69, v69
	v_mul_f32_e32 v65, v71, v71
	v_pk_fma_f32 v[76:77], v[66:67], 0.5, v[96:97] op_sel_hi:[1,0,1]
	v_fmac_f32_e32 v64, v68, v68
	v_fmac_f32_e32 v65, v70, v70
	v_add_f32_e32 v64, v64, v65
	v_mul_f32_e32 v65, v79, v79
	v_mul_f32_e32 v66, v77, v77
	v_fmac_f32_e32 v65, v78, v78
	v_fmac_f32_e32 v66, v76, v76
	v_add_f32_e32 v65, v65, v66
	v_add_f32_e32 v64, v64, v65
	v_add_f32_e32 v64, v100, v64
	ds_bpermute_b32 v65, v171, v64
	v_cvt_pk_bf16_f32 v74, v74, v75
	v_cvt_pk_bf16_f32 v75, v92, v93
	v_cvt_pk_bf16_f32 v66, v68, v69
	v_cvt_pk_bf16_f32 v67, v70, v71
	s_waitcnt lgkmcnt(0)
	v_add_f32_e32 v64, v64, v65
	ds_bpermute_b32 v65, v170, v64
	v_cvt_pk_bf16_f32 v68, v78, v79
	v_cvt_pk_bf16_f32 v69, v76, v77
	global_store_dwordx4 v[106:107], v[72:75], off
	global_store_dwordx4 v[106:107], v[66:69], off offset:256
	s_and_saveexec_b64 s[28:29], s[36:37]
	s_cbranch_execz .LBB0_868
	v_lshlrev_b64 v[66:67], 6, v[104:105]
	v_lshl_add_u64 v[66:67], s[24:25], 0, v[66:67]
	v_lshl_add_u64 v[66:67], s[16:17], 2, v[66:67]
	s_lshl_b32 s40, s50, 2
	s_mov_b32 s41, s5
	v_lshl_add_u64 v[66:67], v[66:67], 0, s[40:41]
	s_waitcnt lgkmcnt(0)
	v_add_f32_e32 v64, v64, v65
	global_store_dword v[66:67], v64, off
.LBB0_868:
	s_or_b64 exec, exec, s[28:29]
	v_or_b32_e32 v72, 16, v88
	v_ashrrev_i32_e32 v73, 31, v72
	s_waitcnt lgkmcnt(0)
	v_lshlrev_b64 v[64:65], 11, v[72:73]
	v_lshl_add_u64 v[64:65], s[22:23], 0, v[64:65]
	v_lshl_add_u64 v[64:65], s[18:19], 1, v[64:65]
	v_lshl_add_u64 v[64:65], v[64:65], 0, s[4:5]
	v_lshl_add_u64 v[74:75], v[64:65], 0, v[144:145]
	s_waitcnt vmcnt(12)
	s_waitcnt vmcnt(12)
	v_lshlrev_b32_e32 v76, 16, v224
	v_and_b32_e32 v77, 0xffff0000, v224
	v_lshlrev_b32_e32 v78, 16, v225
	v_and_b32_e32 v79, 0xffff0000, v225
	v_lshlrev_b32_e32 v84, 16, v226
	v_and_b32_e32 v85, 0xffff0000, v226
	v_lshlrev_b32_e32 v86, 16, v227
	v_and_b32_e32 v87, 0xffff0000, v227
	v_pk_fma_f32 v[60:61], v[60:61], 0.5, v[76:77] op_sel_hi:[1,0,1]
	v_pk_fma_f32 v[62:63], v[62:63], 0.5, v[78:79] op_sel_hi:[1,0,1]
	v_pk_fma_f32 v[76:77], v[58:59], 0.5, v[86:87] op_sel_hi:[1,0,1]
	v_pk_fma_f32 v[58:59], v[56:57], 0.5, v[84:85] op_sel_hi:[1,0,1]
	v_cvt_pk_bf16_f32 v56, v60, v61
	v_mul_f32_e32 v61, v61, v61
	v_fmac_f32_e32 v61, v60, v60
	v_mul_f32_e32 v60, v63, v63
	v_fmac_f32_e32 v60, v62, v62
	v_cvt_pk_bf16_f32 v57, v62, v63
	v_add_f32_e32 v60, v61, v60
	v_mul_f32_e32 v61, v59, v59
	v_mul_f32_e32 v62, v77, v77
	v_fmac_f32_e32 v61, v58, v58
	v_fmac_f32_e32 v62, v76, v76
	v_add_f32_e32 v61, v61, v62
	v_add_f32_e32 v84, v60, v61
	s_waitcnt vmcnt(12)
	v_lshlrev_b32_e32 v60, 16, v228
	v_and_b32_e32 v61, 0xffff0000, v228
	v_lshlrev_b32_e32 v62, 16, v229
	v_and_b32_e32 v63, 0xffff0000, v229
	v_lshlrev_b32_e32 v78, 16, v230
	v_and_b32_e32 v79, 0xffff0000, v230
	v_pk_fma_f32 v[54:55], v[54:55], 0.5, v[62:63] op_sel_hi:[1,0,1]
	v_pk_fma_f32 v[52:53], v[52:53], 0.5, v[60:61] op_sel_hi:[1,0,1]
	v_lshlrev_b32_e32 v80, 16, v231
	v_and_b32_e32 v81, 0xffff0000, v231
	v_pk_fma_f32 v[62:63], v[48:49], 0.5, v[78:79] op_sel_hi:[1,0,1]
	v_mul_f32_e32 v48, v53, v53
	v_mul_f32_e32 v49, v55, v55
	v_pk_fma_f32 v[60:61], v[50:51], 0.5, v[80:81] op_sel_hi:[1,0,1]
	v_fmac_f32_e32 v48, v52, v52
	v_fmac_f32_e32 v49, v54, v54
	v_add_f32_e32 v48, v48, v49
	v_mul_f32_e32 v49, v63, v63
	v_mul_f32_e32 v50, v61, v61
	v_fmac_f32_e32 v49, v62, v62
	v_fmac_f32_e32 v50, v60, v60
	v_add_f32_e32 v49, v49, v50
	v_add_f32_e32 v48, v48, v49
	v_add_f32_e32 v48, v84, v48
	ds_bpermute_b32 v49, v171, v48
	v_cvt_pk_bf16_f32 v58, v58, v59
	v_cvt_pk_bf16_f32 v59, v76, v77
	v_cvt_pk_bf16_f32 v50, v52, v53
	v_cvt_pk_bf16_f32 v51, v54, v55
	s_waitcnt lgkmcnt(0)
	v_add_f32_e32 v48, v48, v49
	ds_bpermute_b32 v49, v170, v48
	v_cvt_pk_bf16_f32 v52, v62, v63
	v_cvt_pk_bf16_f32 v53, v60, v61
	global_store_dwordx4 v[90:91], v[56:59], off
	global_store_dwordx4 v[90:91], v[50:53], off offset:256
	s_and_saveexec_b64 s[28:29], s[36:37]
	s_cbranch_execz .LBB0_870
	v_lshlrev_b64 v[50:51], 6, v[88:89]
	v_lshl_add_u64 v[50:51], s[24:25], 0, v[50:51]
	v_lshl_add_u64 v[50:51], s[16:17], 2, v[50:51]
	s_lshl_b32 s40, s50, 2
	s_mov_b32 s41, s5
	v_lshl_add_u64 v[50:51], v[50:51], 0, s[40:41]
	s_waitcnt lgkmcnt(0)
	v_add_f32_e32 v48, v48, v49
	global_store_dword v[50:51], v48, off
; __device__ __forceinline__ u32x2 pack4(f32x4 v) { u32x2 w; w.x = cvt_pk_bf16(v[0], v[1]); w.y = cvt_pk_bf16(v[2], v[3]); return w; }
;     __device__ __forceinline__ void gload(Grp& h, size_t off) const {
;         if constexpr (F32IN) { h.f[0] = *(const f32x4*)(hin + off); h.f[1] = *(const f32x4*)(hin + off + 4); h.f[2] = *(const f32x4*)(hin + off + HALF); h.f[3] = *(const f32x4*)(hin + off + HALF + 4); }
;         else { const u32x4 a = *(const u32x4*)(xa + off), b = *(const u32x4*)(xa + off + HALF); h.f[0] = __builtin_bit_cast(f32x4, a); h.f[2] = __builtin_bit_cast(f32x4, b); }
;     }
;     __device__ __forceinline__ void unpack(const Grp& h, int bj, f32x4& v0, f32x4& v1) const {
;         if constexpr (F32IN) { v0 = h.f[2 * bj]; v1 = h.f[2 * bj + 1]; }
;         else { const u32x4 w = __builtin_bit_cast(u32x4, h.f[2 * bj]);
;             v0[0] = __uint_as_float(w.x << 16); v0[1] = __uint_as_float(w.x & 0xffff0000u); v0[2] = __uint_as_float(w.y << 16); v0[3] = __uint_as_float(w.y & 0xffff0000u);
;             v1[0] = __uint_as_float(w.z << 16); v1[1] = __uint_as_float(w.z & 0xffff0000u); v1[2] = __uint_as_float(w.w << 16); v1[3] = __uint_as_float(w.w & 0xffff0000u); }
;     }
;     __device__ __forceinline__ void operator()(const f32x4 (&acc)[2][2][4][2], const Unit& u, int wr, int wc, int fr, int fq) const {
;         Grp h[2];
;         gload(h[0], goff(u, 0, wr, wc, fr, fq));
; #pragma unroll
;         for (int g = 0; g < 8; ++g) {
;             const int ai = g >> 2, m = g & 3; const size_t off = goff(u, g, wr, wc, fr, fq);
;             if (g < 7) gload(h[(g + 1) & 1], goff(u, g + 1, wr, wc, fr, fq));
;             float sq = 0.f;
; #pragma unroll
;             for (int bj = 0; bj < 2; ++bj) { const size_t o = off + bj * HALF; f32x4 h0, h1; unpack(h[g & 1], bj, h0, h1);
;                 h0 = h0 + acc[ai][bj][m][0] * alpha; h1 = h1 + acc[ai][bj][m][1] * alpha;
;                 const u32x2 p0 = pack4(h0), p1 = pack4(h1); u32x4 w; w.x = p0.x; w.y = p0.y; w.z = p1.x; w.w = p1.y; *(u32x4*)(xa + o) = w;
;                 sq += ((h0[0] * h0[0] + h0[1] * h0[1]) + (h0[2] * h0[2] + h0[3] * h0[3])) + ((h1[0] * h1[0] + h1[1] * h1[1]) + (h1[2] * h1[2] + h1[3] * h1[3])); }
;             sq += __shfl_xor(sq, 16); sq += __shfl_xor(sq, 32);
;             if (fq == 0) ssout[(size_t)(u.pm * BM + ai * HALF + wr * 64 + m * 16 + fr) * 16 + u.pn * 4 + wc] = sq;
.LBB0_870:
	s_or_b64 exec, exec, s[28:29]
	v_or_b32_e32 v56, 32, v88
	v_ashrrev_i32_e32 v57, 31, v56
	s_waitcnt lgkmcnt(0)
	v_lshlrev_b64 v[48:49], 11, v[56:57]
	v_lshl_add_u64 v[48:49], s[22:23], 0, v[48:49]
	v_lshl_add_u64 v[48:49], s[18:19], 1, v[48:49]
	v_lshl_add_u64 v[48:49], v[48:49], 0, s[4:5]
	v_lshl_add_u64 v[58:59], v[48:49], 0, v[144:145]
	s_waitcnt vmcnt(12)
	s_waitcnt vmcnt(12)
	v_lshlrev_b32_e32 v60, 16, v232
	v_and_b32_e32 v61, 0xffff0000, v232
	v_lshlrev_b32_e32 v62, 16, v233
	v_and_b32_e32 v63, 0xffff0000, v233
	v_lshlrev_b32_e32 v68, 16, v234
	v_and_b32_e32 v69, 0xffff0000, v234
	v_lshlrev_b32_e32 v70, 16, v235
	v_and_b32_e32 v71, 0xffff0000, v235
	v_pk_fma_f32 v[44:45], v[44:45], 0.5, v[60:61] op_sel_hi:[1,0,1]
	v_pk_fma_f32 v[46:47], v[46:47], 0.5, v[62:63] op_sel_hi:[1,0,1]
	v_pk_fma_f32 v[60:61], v[42:43], 0.5, v[70:71] op_sel_hi:[1,0,1]
	v_pk_fma_f32 v[42:43], v[40:41], 0.5, v[68:69] op_sel_hi:[1,0,1]
	v_cvt_pk_bf16_f32 v40, v44, v45
	v_mul_f32_e32 v45, v45, v45
	v_fmac_f32_e32 v45, v44, v44
	v_mul_f32_e32 v44, v47, v47
	v_fmac_f32_e32 v44, v46, v46
	v_cvt_pk_bf16_f32 v41, v46, v47
	v_add_f32_e32 v44, v45, v44
	v_mul_f32_e32 v45, v43, v43
	v_mul_f32_e32 v46, v61, v61
	v_fmac_f32_e32 v45, v42, v42
	v_fmac_f32_e32 v46, v60, v60
	v_add_f32_e32 v45, v45, v46
	v_add_f32_e32 v68, v44, v45
	s_waitcnt vmcnt(12)
	v_lshlrev_b32_e32 v44, 16, v236
	v_and_b32_e32 v45, 0xffff0000, v236
	v_lshlrev_b32_e32 v46, 16, v237
	v_and_b32_e32 v47, 0xffff0000, v237
	v_lshlrev_b32_e32 v62, 16, v238
	v_and_b32_e32 v63, 0xffff0000, v238
	v_pk_fma_f32 v[38:39], v[38:39], 0.5, v[46:47] op_sel_hi:[1,0,1]
	v_pk_fma_f32 v[36:37], v[36:37], 0.5, v[44:45] op_sel_hi:[1,0,1]
	v_lshlrev_b32_e32 v64, 16, v239
	v_and_b32_e32 v65, 0xffff0000, v239
	v_pk_fma_f32 v[46:47], v[32:33], 0.5, v[62:63] op_sel_hi:[1,0,1]
	v_mul_f32_e32 v32, v37, v37
	v_mul_f32_e32 v33, v39, v39
	v_pk_fma_f32 v[44:45], v[34:35], 0.5, v[64:65] op_sel_hi:[1,0,1]
	v_fmac_f32_e32 v32, v36, v36
	v_fmac_f32_e32 v33, v38, v38
	v_add_f32_e32 v32, v32, v33
	v_mul_f32_e32 v33, v47, v47
	v_mul_f32_e32 v34, v45, v45
	v_fmac_f32_e32 v33, v46, v46
	v_fmac_f32_e32 v34, v44, v44
	v_add_f32_e32 v33, v33, v34
	v_add_f32_e32 v32, v32, v33
	v_add_f32_e32 v32, v68, v32
	ds_bpermute_b32 v33, v171, v32
	v_cvt_pk_bf16_f32 v42, v42, v43
	v_cvt_pk_bf16_f32 v43, v60, v61
	v_cvt_pk_bf16_f32 v34, v36, v37
	v_cvt_pk_bf16_f32 v35, v38, v39
	s_waitcnt lgkmcnt(0)
	v_add_f32_e32 v32, v32, v33
	ds_bpermute_b32 v33, v170, v32
	v_cvt_pk_bf16_f32 v36, v46, v47
	v_cvt_pk_bf16_f32 v37, v44, v45
	global_store_dwordx4 v[74:75], v[40:43], off
	global_store_dwordx4 v[74:75], v[34:37], off offset:256
	s_and_saveexec_b64 s[28:29], s[36:37]
	s_cbranch_execz .LBB0_872
	v_lshlrev_b64 v[34:35], 6, v[72:73]
	v_lshl_add_u64 v[34:35], s[24:25], 0, v[34:35]
	v_lshl_add_u64 v[34:35], s[16:17], 2, v[34:35]
	s_lshl_b32 s40, s50, 2
	s_mov_b32 s41, s5
	v_lshl_add_u64 v[34:35], v[34:35], 0, s[40:41]
	s_waitcnt lgkmcnt(0)
	v_add_f32_e32 v32, v32, v33
	global_store_dword v[34:35], v32, off
; __device__ __forceinline__ u32x2 pack4(f32x4 v) { u32x2 w; w.x = cvt_pk_bf16(v[0], v[1]); w.y = cvt_pk_bf16(v[2], v[3]); return w; }
;     __device__ __forceinline__ void gload(Grp& h, size_t off) const {
;         if constexpr (F32IN) { h.f[0] = *(const f32x4*)(hin + off); h.f[1] = *(const f32x4*)(hin + off + 4); h.f[2] = *(const f32x4*)(hin + off + HALF); h.f[3] = *(const f32x4*)(hin + off + HALF + 4); }
;         else { const u32x4 a = *(const u32x4*)(xa + off), b = *(const u32x4*)(xa + off + HALF); h.f[0] = __builtin_bit_cast(f32x4, a); h.f[2] = __builtin_bit_cast(f32x4, b); }
;     }
;     __device__ __forceinline__ void unpack(const Grp& h, int bj, f32x4& v0, f32x4& v1) const {
;         if constexpr (F32IN) { v0 = h.f[2 * bj]; v1 = h.f[2 * bj + 1]; }
;         else { const u32x4 w = __builtin_bit_cast(u32x4, h.f[2 * bj]);
;             v0[0] = __uint_as_float(w.x << 16); v0[1] = __uint_as_float(w.x & 0xffff0000u); v0[2] = __uint_as_float(w.y << 16); v0[3] = __uint_as_float(w.y & 0xffff0000u);
;             v1[0] = __uint_as_float(w.z << 16); v1[1] = __uint_as_float(w.z & 0xffff0000u); v1[2] = __uint_as_float(w.w << 16); v1[3] = __uint_as_float(w.w & 0xffff0000u); }
;     }
;     __device__ __forceinline__ void operator()(const f32x4 (&acc)[2][2][4][2], const Unit& u, int wr, int wc, int fr, int fq) const {
;         Grp h[2];
;         gload(h[0], goff(u, 0, wr, wc, fr, fq));
; #pragma unroll
;         for (int g = 0; g < 8; ++g) {
;             const int ai = g >> 2, m = g & 3; const size_t off = goff(u, g, wr, wc, fr, fq);
;             if (g < 7) gload(h[(g + 1) & 1], goff(u, g + 1, wr, wc, fr, fq));
;             float sq = 0.f;
; #pragma unroll
;             for (int bj = 0; bj < 2; ++bj) { const size_t o = off + bj * HALF; f32x4 h0, h1; unpack(h[g & 1], bj, h0, h1);
;                 h0 = h0 + acc[ai][bj][m][0] * alpha; h1 = h1 + acc[ai][bj][m][1] * alpha;
;                 const u32x2 p0 = pack4(h0), p1 = pack4(h1); u32x4 w; w.x = p0.x; w.y = p0.y; w.z = p1.x; w.w = p1.y; *(u32x4*)(xa + o) = w;
;                 sq += ((h0[0] * h0[0] + h0[1] * h0[1]) + (h0[2] * h0[2] + h0[3] * h0[3])) + ((h1[0] * h1[0] + h1[1] * h1[1]) + (h1[2] * h1[2] + h1[3] * h1[3])); }
;             sq += __shfl_xor(sq, 16); sq += __shfl_xor(sq, 32);
;             if (fq == 0) ssout[(size_t)(u.pm * BM + ai * HALF + wr * 64 + m * 16 + fr) * 16 + u.pn * 4 + wc] = sq;
.LBB0_872:
	s_or_b64 exec, exec, s[28:29]
	v_or_b32_e32 v40, 48, v88
	v_ashrrev_i32_e32 v41, 31, v40
	s_waitcnt lgkmcnt(0)
	v_lshlrev_b64 v[32:33], 11, v[40:41]
	v_lshl_add_u64 v[32:33], s[22:23], 0, v[32:33]
	v_lshl_add_u64 v[32:33], s[18:19], 1, v[32:33]
	v_lshl_add_u64 v[32:33], v[32:33], 0, s[4:5]
	v_lshl_add_u64 v[42:43], v[32:33], 0, v[144:145]
	global_load_dwordx4 v[36:39], v[42:43], off
	global_load_dwordx4 v[32:35], v[42:43], off offset:256
	s_waitcnt vmcnt(14)
	s_waitcnt vmcnt(14)
	v_lshlrev_b32_e32 v44, 16, v240
	v_and_b32_e32 v45, 0xffff0000, v240
	v_lshlrev_b32_e32 v46, 16, v241
	v_and_b32_e32 v47, 0xffff0000, v241
	v_lshlrev_b32_e32 v52, 16, v242
	v_and_b32_e32 v53, 0xffff0000, v242
	v_lshlrev_b32_e32 v54, 16, v243
	v_and_b32_e32 v55, 0xffff0000, v243
	v_pk_fma_f32 v[28:29], v[28:29], 0.5, v[44:45] op_sel_hi:[1,0,1]
	v_pk_fma_f32 v[30:31], v[30:31], 0.5, v[46:47] op_sel_hi:[1,0,1]
	v_pk_fma_f32 v[44:45], v[26:27], 0.5, v[54:55] op_sel_hi:[1,0,1]
	v_pk_fma_f32 v[26:27], v[24:25], 0.5, v[52:53] op_sel_hi:[1,0,1]
	v_cvt_pk_bf16_f32 v24, v28, v29
	v_mul_f32_e32 v29, v29, v29
	v_fmac_f32_e32 v29, v28, v28
	v_mul_f32_e32 v28, v31, v31
	v_fmac_f32_e32 v28, v30, v30
	v_cvt_pk_bf16_f32 v25, v30, v31
	v_add_f32_e32 v28, v29, v28
	v_mul_f32_e32 v29, v27, v27
	v_mul_f32_e32 v30, v45, v45
	v_fmac_f32_e32 v29, v26, v26
	v_fmac_f32_e32 v30, v44, v44
	v_add_f32_e32 v29, v29, v30
	v_add_f32_e32 v52, v28, v29
	s_waitcnt vmcnt(14)
	v_lshlrev_b32_e32 v28, 16, v244
	v_and_b32_e32 v29, 0xffff0000, v244
	v_lshlrev_b32_e32 v30, 16, v245
	v_and_b32_e32 v31, 0xffff0000, v245
	v_lshlrev_b32_e32 v46, 16, v246
	v_and_b32_e32 v47, 0xffff0000, v246
	v_pk_fma_f32 v[22:23], v[22:23], 0.5, v[30:31] op_sel_hi:[1,0,1]
	v_pk_fma_f32 v[20:21], v[20:21], 0.5, v[28:29] op_sel_hi:[1,0,1]
	v_lshlrev_b32_e32 v48, 16, v247
	v_and_b32_e32 v49, 0xffff0000, v247
	v_pk_fma_f32 v[30:31], v[16:17], 0.5, v[46:47] op_sel_hi:[1,0,1]
	v_mul_f32_e32 v16, v21, v21
	v_mul_f32_e32 v17, v23, v23
	v_pk_fma_f32 v[28:29], v[18:19], 0.5, v[48:49] op_sel_hi:[1,0,1]
	v_fmac_f32_e32 v16, v20, v20
	v_fmac_f32_e32 v17, v22, v22
	v_add_f32_e32 v16, v16, v17
	v_mul_f32_e32 v17, v31, v31
	v_mul_f32_e32 v18, v29, v29
	v_fmac_f32_e32 v17, v30, v30
	v_fmac_f32_e32 v18, v28, v28
	v_add_f32_e32 v17, v17, v18
	v_add_f32_e32 v16, v16, v17
	v_add_f32_e32 v16, v52, v16
	ds_bpermute_b32 v17, v171, v16
	v_cvt_pk_bf16_f32 v26, v26, v27
	v_cvt_pk_bf16_f32 v27, v44, v45
	v_cvt_pk_bf16_f32 v18, v20, v21
	v_cvt_pk_bf16_f32 v19, v22, v23
	s_waitcnt lgkmcnt(0)
	v_add_f32_e32 v16, v16, v17
	ds_bpermute_b32 v17, v170, v16
	v_cvt_pk_bf16_f32 v20, v30, v31
	v_cvt_pk_bf16_f32 v21, v28, v29
	global_store_dwordx4 v[58:59], v[24:27], off
	global_store_dwordx4 v[58:59], v[18:21], off offset:256
	s_and_saveexec_b64 s[18:19], s[36:37]
	s_cbranch_execz .LBB0_874
	v_lshlrev_b64 v[18:19], 6, v[56:57]
	v_lshl_add_u64 v[18:19], s[24:25], 0, v[18:19]
	v_lshl_add_u64 v[18:19], s[16:17], 2, v[18:19]
	s_lshl_b32 s4, s50, 2
	v_lshl_add_u64 v[18:19], v[18:19], 0, s[4:5]
	s_waitcnt lgkmcnt(0)
	v_add_f32_e32 v16, v16, v17
	global_store_dword v[18:19], v16, off
.LBB0_874:
	s_or_b64 exec, exec, s[18:19]
	s_waitcnt vmcnt(2)
	v_lshlrev_b32_e32 v16, 16, v36
	s_waitcnt lgkmcnt(0)
	v_and_b32_e32 v17, 0xffff0000, v36
	v_lshlrev_b32_e32 v18, 16, v37
	v_and_b32_e32 v19, 0xffff0000, v37
	v_lshlrev_b32_e32 v20, 16, v38
	v_and_b32_e32 v21, 0xffff0000, v38
	v_lshlrev_b32_e32 v22, 16, v39
	v_and_b32_e32 v23, 0xffff0000, v39
	v_pk_fma_f32 v[12:13], v[12:13], 0.5, v[16:17] op_sel_hi:[1,0,1]
	v_pk_fma_f32 v[14:15], v[14:15], 0.5, v[18:19] op_sel_hi:[1,0,1]
	v_pk_fma_f32 v[16:17], v[10:11], 0.5, v[22:23] op_sel_hi:[1,0,1]
	v_pk_fma_f32 v[10:11], v[8:9], 0.5, v[20:21] op_sel_hi:[1,0,1]
	v_cvt_pk_bf16_f32 v8, v12, v13
	v_mul_f32_e32 v13, v13, v13
	v_fmac_f32_e32 v13, v12, v12
	v_mul_f32_e32 v12, v15, v15
	v_fmac_f32_e32 v12, v14, v14
	v_cvt_pk_bf16_f32 v9, v14, v15
	v_add_f32_e32 v12, v13, v12
	v_mul_f32_e32 v13, v11, v11
	v_mul_f32_e32 v14, v17, v17
	v_fmac_f32_e32 v13, v10, v10
	v_fmac_f32_e32 v14, v16, v16
	v_add_f32_e32 v13, v13, v14
	v_add_f32_e32 v22, v12, v13
	s_waitcnt vmcnt(2)
	v_lshlrev_b32_e32 v12, 16, v32
	v_and_b32_e32 v13, 0xffff0000, v32
	v_lshlrev_b32_e32 v14, 16, v33
	v_and_b32_e32 v15, 0xffff0000, v33
	v_lshlrev_b32_e32 v18, 16, v34
	v_and_b32_e32 v19, 0xffff0000, v34
	v_pk_fma_f32 v[6:7], v[6:7], 0.5, v[14:15] op_sel_hi:[1,0,1]
	v_pk_fma_f32 v[4:5], v[4:5], 0.5, v[12:13] op_sel_hi:[1,0,1]
	v_lshlrev_b32_e32 v20, 16, v35
	v_and_b32_e32 v21, 0xffff0000, v35
	v_pk_fma_f32 v[14:15], v[0:1], 0.5, v[18:19] op_sel_hi:[1,0,1]
	v_mul_f32_e32 v0, v5, v5
	v_mul_f32_e32 v1, v7, v7
	v_pk_fma_f32 v[12:13], v[2:3], 0.5, v[20:21] op_sel_hi:[1,0,1]
	v_fmac_f32_e32 v0, v4, v4
	v_fmac_f32_e32 v1, v6, v6
	v_add_f32_e32 v0, v0, v1
	v_mul_f32_e32 v1, v15, v15
	v_mul_f32_e32 v2, v13, v13
	v_fmac_f32_e32 v1, v14, v14
	v_fmac_f32_e32 v2, v12, v12
	v_add_f32_e32 v1, v1, v2
	v_add_f32_e32 v0, v0, v1
	v_add_f32_e32 v0, v22, v0
	ds_bpermute_b32 v1, v171, v0
	v_cvt_pk_bf16_f32 v10, v10, v11
	v_cvt_pk_bf16_f32 v11, v16, v17
	v_cvt_pk_bf16_f32 v2, v4, v5
	s_waitcnt lgkmcnt(0)
	v_add_f32_e32 v0, v0, v1
	ds_bpermute_b32 v1, v170, v0
	v_cvt_pk_bf16_f32 v3, v6, v7
	v_cvt_pk_bf16_f32 v4, v14, v15
	v_cvt_pk_bf16_f32 v5, v12, v13
	global_store_dwordx4 v[42:43], v[8:11], off
	global_store_dwordx4 v[42:43], v[2:5], off offset:256
	s_and_saveexec_b64 s[18:19], s[36:37]
	s_cbranch_execz .LBB0_876
	v_lshlrev_b64 v[2:3], 6, v[40:41]
	v_lshl_add_u64 v[2:3], s[24:25], 0, v[2:3]
	v_lshl_add_u64 v[2:3], s[16:17], 2, v[2:3]
	s_lshl_b32 s4, s50, 2
	v_lshl_add_u64 v[2:3], v[2:3], 0, s[4:5]
	s_waitcnt lgkmcnt(0)
	v_add_f32_e32 v0, v0, v1
	global_store_dword v[2:3], v0, off
